# conv group LayerNorm gain/bias vectors loaded once before the unit loop instead of per token
# speedup vs baseline: 1.0410x; 1.0032x over previous
; #define LAS __attribute__((address_space(3)))
; __device__ __forceinline__ void conv_phase(LAS unsigned char* lds, const bf16_t* PROJ, const float* cw, const float* cb, const float* lg, const float* lb, bf16_t* MIXIN, int G, int tid) {
;     LAS float* U = (LAS float*)lds;
;     for (int u = blockIdx.x; u < M / 32; u += G) {
;         asm volatile("" : "+v"(tid));
;         const int lane = tid & 63, wave = __builtin_amdgcn_readfirstlane(tid >> 6);
;         const int row0 = u * 32, t0 = row0 % SEQ;
;         const int c = tid;
;         float w[31];
; #pragma unroll
;         for (int k = 0; k < 31; ++k) w[k] = cw[k * 512 + c];
;         const float bias = cb[c];
; #pragma unroll
;         for (int pass = 0; pass < 8; ++pass) { const int rr = pass * 8 + wave;
;             if (rr < 62) { f32x4 o0 = (f32x4){0.f, 0.f, 0.f, 0.f}, o1 = o0;
;                 if (t0 - 30 + rr >= 0) { const u32x4 a = *(const u32x4*)(PROJ + (size_t)(row0 - 30 + rr) * PROJ_LD + 8 * lane);
;                     o0 = (f32x4){__uint_as_float(a[0] << 16), __uint_as_float(a[0] & 0xffff0000u), __uint_as_float(a[1] << 16), __uint_as_float(a[1] & 0xffff0000u)};
;                     o1 = (f32x4){__uint_as_float(a[2] << 16), __uint_as_float(a[2] & 0xffff0000u), __uint_as_float(a[3] << 16), __uint_as_float(a[3] & 0xffff0000u)}; }
;                 *(LAS f32x4*)(U + rr * 512 + 8 * lane) = o0; *(LAS f32x4*)(U + rr * 512 + 8 * lane + 4) = o1; } }
;         __syncthreads();
;         float y[32];
; #pragma unroll
;         for (int blk = 0; blk < 4; ++blk) { float win[38];
; #pragma unroll
;             for (int x = 0; x < 38; ++x) win[x] = U[(8 * blk + x) * 512 + c];
.LBB0_427:
	s_andn2_b64 vcc, exec, s[4:5]
	s_mov_b64 s[20:21], 0
	s_cbranch_vccnz .LBB0_542
	v_readlane_b32 s4, v254, 1
	s_cmp_gt_i32 s4, 0
	s_mov_b64 s[4:5], -1
	s_cbranch_scc0 .LBB0_540
	v_readlane_b32 s4, v253, 46
	v_readlane_b32 s5, v255, 14
	s_cmp_ge_u32 s5, s4
	v_readlane_b32 s4, v250, 60
	s_cselect_b64 s[8:9], -1, 0
	v_readlane_b32 s5, v250, 61
	v_readlane_b32 s6, v250, 58
	s_or_b64 s[4:5], s[4:5], s[8:9]
	v_readlane_b32 s7, v250, 59
	s_and_b64 s[4:5], s[6:7], s[4:5]
	s_andn2_b64 vcc, exec, s[4:5]
	s_cbranch_vccnz .LBB0_465
	v_readlane_b32 s6, v250, 62
	v_readlane_b32 s7, v250, 63
	s_mov_b32 s10, 7
	s_mov_b32 s12, 8
	s_mov_b32 s14, 9
	s_mov_b32 s4, 10
	s_andn2_b64 vcc, exec, s[6:7]
	s_cbranch_vccnz .LBB0_465
	s_ashr_i32 s11, s10, 31
	s_lshl_b64 s[6:7], s[10:11], 3
	s_add_u32 s6, s0, s6
	s_addc_u32 s7, s1, s7
	s_load_dwordx2 s[6:7], s[6:7], 0x0
	v_readlane_b32 s10, v255, 10
	v_readlane_b32 s11, v255, 11
	v_readlane_b32 s16, v255, 12
	v_readlane_b32 s17, v255, 13
	s_waitcnt lgkmcnt(0)
	s_add_u32 s10, s6, s10
	s_addc_u32 s11, s7, s11
	s_ashr_i32 s13, s12, 31
	s_lshl_b64 s[6:7], s[12:13], 3
	s_add_u32 s6, s0, s6
	s_addc_u32 s7, s1, s7
	s_load_dwordx2 s[6:7], s[6:7], 0x0
	s_waitcnt vmcnt(0)
	v_mov_b32_e32 v8, v170
	s_waitcnt lgkmcnt(0)
	s_add_u32 s12, s6, s16
	s_addc_u32 s13, s7, s17
	s_ashr_i32 s15, s14, 31
	s_lshl_b64 s[6:7], s[14:15], 3
	s_add_u32 s6, s0, s6
	s_addc_u32 s7, s1, s7
	s_load_dwordx2 s[6:7], s[6:7], 0x0
	s_waitcnt lgkmcnt(0)
	s_add_u32 s14, s6, s16
	s_addc_u32 s15, s7, s17
	s_ashr_i32 s5, s4, 31
	s_lshl_b64 s[4:5], s[4:5], 3
	s_add_u32 s4, s0, s4
	s_addc_u32 s5, s1, s5
	s_load_dwordx2 s[4:5], s[4:5], 0x0
	v_readlane_b32 s6, v253, 22
	s_mov_b32 s7, s2
	s_waitcnt lgkmcnt(0)
	s_add_u32 s16, s4, s16
	s_addc_u32 s17, s5, s17
	v_lshlrev_b32_e32 v116, 5, v172
	global_load_dwordx4 v[100:103], v116, s[14:15] offset:16
	global_load_dwordx4 v[104:107], v116, s[14:15]
	global_load_dwordx4 v[108:111], v116, s[16:17] offset:16
	global_load_dwordx4 v[112:115], v116, s[16:17]
	s_waitcnt vmcnt(0)
	s_branch .LBB0_434
.LBB0_433:
	v_lshl_add_u32 v62, v8, 2, 0
	v_add_u32_e32 v63, 0x10000, v62
	v_add_u32_e32 v74, 0x13800, v62
	v_add_u32_e32 v81, 0x17000, v62
	v_add_u32_e32 v88, 0x1a800, v62
	v_add_u32_e32 v95, 0x1e000, v62
	v_lshlrev_b32_e32 v61, 3, v12
	s_waitcnt lgkmcnt(0)
	s_barrier
	ds_read2st64_b32 v[70:71], v62 offset1:8
	ds_read2st64_b32 v[72:73], v62 offset0:16 offset1:24
	ds_read2st64_b32 v[28:29], v62 offset0:32 offset1:40
	ds_read2st64_b32 v[26:27], v62 offset0:48 offset1:56
	ds_read2st64_b32 v[24:25], v62 offset0:64 offset1:72
	ds_read2st64_b32 v[22:23], v62 offset0:80 offset1:88
	ds_read2st64_b32 v[20:21], v62 offset0:96 offset1:104
	ds_read2st64_b32 v[18:19], v62 offset0:112 offset1:120
	ds_read2st64_b32 v[16:17], v62 offset0:128 offset1:136
	ds_read2st64_b32 v[14:15], v62 offset0:144 offset1:152
	ds_read2st64_b32 v[12:13], v62 offset0:160 offset1:168
	ds_read2st64_b32 v[10:11], v62 offset0:176 offset1:184
	ds_read2st64_b32 v[6:7], v62 offset0:192 offset1:200
	ds_read2st64_b32 v[4:5], v62 offset0:208 offset1:216
	ds_read2st64_b32 v[2:3], v62 offset0:224 offset1:232
	ds_read2st64_b32 v[0:1], v62 offset0:240 offset1:248
	ds_read_b32 v64, v63
	ds_read_b32 v74, v74
	ds_read_b32 v81, v81
	ds_read_b32 v88, v88
	ds_read_b32 v95, v95
	v_add_u32_e32 v63, 0x10800, v62
	v_add_u32_e32 v75, 0x14000, v62
	v_add_u32_e32 v82, 0x17800, v62
	v_add_u32_e32 v89, 0x1b000, v62
	v_add_u32_e32 v96, 0x1e800, v62
	ds_read_b32 v65, v63
	ds_read_b32 v75, v75
	ds_read_b32 v82, v82
	ds_read_b32 v89, v89
	ds_read_b32 v96, v96
	v_add_u32_e32 v63, 0x11000, v62
	v_add_u32_e32 v76, 0x14800, v62
	v_add_u32_e32 v83, 0x18000, v62
	v_add_u32_e32 v90, 0x1b800, v62
	ds_read_b32 v66, v63
	ds_read_b32 v76, v76
	ds_read_b32 v83, v83
	ds_read_b32 v90, v90
	v_add_u32_e32 v63, 0x11800, v62
	v_add_u32_e32 v77, 0x15000, v62
	v_add_u32_e32 v84, 0x18800, v62
	v_add_u32_e32 v91, 0x1c000, v62
	ds_read_b32 v67, v63
	ds_read_b32 v77, v77
	ds_read_b32 v84, v84
	ds_read_b32 v91, v91
	v_add_u32_e32 v63, 0x12000, v62
	v_add_u32_e32 v78, 0x15800, v62
	v_add_u32_e32 v85, 0x19000, v62
	v_add_u32_e32 v92, 0x1c800, v62
	ds_read_b32 v68, v63
	ds_read_b32 v78, v78
	ds_read_b32 v85, v85
	ds_read_b32 v92, v92
	v_add_u32_e32 v63, 0x12800, v62
	v_add_u32_e32 v79, 0x16000, v62
	v_add_u32_e32 v86, 0x19800, v62
	v_add_u32_e32 v93, 0x1d000, v62
	ds_read_b32 v69, v63
	ds_read_b32 v79, v79
	ds_read_b32 v86, v86
	ds_read_b32 v93, v93
	s_waitcnt vmcnt(0) lgkmcnt(14)
; __device__ __forceinline__ void conv_phase(LAS unsigned char* lds, const bf16_t* PROJ, const float* cw, const float* cb, const float* lg, const float* lb, bf16_t* MIXIN, int G, int tid) {
;     ...
;             for (int o = 0; o < 8; ++o) { float acc = bias;
; #pragma unroll
;                 for (int k = 0; k < 31; ++k) acc += w[k] * win[o + k];
;                 y[8 * blk + o] = acc; } }
	v_fma_f32 v63, v36, v70, v49
	v_fmac_f32_e32 v63, v35, v71
	v_fma_f32 v70, v36, v71, v49
	v_fmac_f32_e32 v63, v34, v72
	v_fmac_f32_e32 v70, v35, v72
	v_fma_f32 v71, v36, v72, v49
	v_fmac_f32_e32 v63, v33, v73
	v_fmac_f32_e32 v70, v34, v73
	v_fmac_f32_e32 v71, v35, v73
	v_fma_f32 v72, v36, v73, v49
	v_fmac_f32_e32 v63, v31, v28
	v_fmac_f32_e32 v70, v33, v28
	v_fmac_f32_e32 v71, v34, v28
	v_fmac_f32_e32 v72, v35, v28
	v_fma_f32 v28, v36, v28, v49
	v_fmac_f32_e32 v63, v9, v29
	v_fmac_f32_e32 v70, v31, v29
	v_fmac_f32_e32 v71, v33, v29
	v_fmac_f32_e32 v72, v34, v29
	v_fmac_f32_e32 v28, v35, v29
	v_fma_f32 v29, v36, v29, v49
	v_fmac_f32_e32 v63, v32, v26
	v_fmac_f32_e32 v70, v9, v26
	v_fmac_f32_e32 v71, v31, v26
	v_fmac_f32_e32 v72, v33, v26
	v_fmac_f32_e32 v28, v34, v26
	v_fmac_f32_e32 v29, v35, v26
	v_fma_f32 v26, v36, v26, v49
	v_fmac_f32_e32 v63, v30, v27
	v_fmac_f32_e32 v70, v32, v27
	v_fmac_f32_e32 v71, v9, v27
	v_fmac_f32_e32 v72, v31, v27
	v_fmac_f32_e32 v28, v33, v27
	v_fmac_f32_e32 v29, v34, v27
	v_fmac_f32_e32 v26, v35, v27
	v_fma_f32 v27, v36, v27, v49
	v_fmac_f32_e32 v63, v44, v24
	v_fmac_f32_e32 v70, v30, v24
	v_fmac_f32_e32 v71, v32, v24
	v_fmac_f32_e32 v72, v9, v24
	v_fmac_f32_e32 v28, v31, v24
	v_fmac_f32_e32 v29, v33, v24
	v_fmac_f32_e32 v26, v34, v24
	v_fmac_f32_e32 v27, v35, v24
	v_fma_f32 v24, v36, v24, v49
	v_fmac_f32_e32 v63, v43, v25
	v_fmac_f32_e32 v70, v44, v25
	v_fmac_f32_e32 v71, v30, v25
	v_fmac_f32_e32 v72, v32, v25
	v_fmac_f32_e32 v28, v9, v25
	v_fmac_f32_e32 v29, v31, v25
	v_fmac_f32_e32 v26, v33, v25
	v_fmac_f32_e32 v27, v34, v25
	v_fmac_f32_e32 v24, v35, v25
	v_fma_f32 v25, v36, v25, v49
	v_fmac_f32_e32 v63, v42, v22
	v_fmac_f32_e32 v70, v43, v22
	v_fmac_f32_e32 v71, v44, v22
	v_fmac_f32_e32 v72, v30, v22
	v_fmac_f32_e32 v28, v32, v22
	v_fmac_f32_e32 v29, v9, v22
	v_fmac_f32_e32 v26, v31, v22
	v_fmac_f32_e32 v27, v33, v22
	v_fmac_f32_e32 v24, v34, v22
	v_fmac_f32_e32 v25, v35, v22
	v_fma_f32 v22, v36, v22, v49
	v_fmac_f32_e32 v63, v41, v23
	v_fmac_f32_e32 v70, v42, v23
	v_fmac_f32_e32 v71, v43, v23
	v_fmac_f32_e32 v72, v44, v23
	v_fmac_f32_e32 v28, v30, v23
	v_fmac_f32_e32 v29, v32, v23
	v_fmac_f32_e32 v26, v9, v23
	v_fmac_f32_e32 v27, v31, v23
	v_fmac_f32_e32 v24, v33, v23
	v_fmac_f32_e32 v25, v34, v23
	v_fmac_f32_e32 v22, v35, v23
	v_fma_f32 v23, v36, v23, v49
	v_fmac_f32_e32 v63, v39, v20
	v_fmac_f32_e32 v70, v41, v20
	v_fmac_f32_e32 v71, v42, v20
	v_fmac_f32_e32 v72, v43, v20
	v_fmac_f32_e32 v28, v44, v20
	v_fmac_f32_e32 v29, v30, v20
	v_fmac_f32_e32 v26, v32, v20
	v_fmac_f32_e32 v27, v9, v20
	v_fmac_f32_e32 v24, v31, v20
	v_fmac_f32_e32 v25, v33, v20
	v_fmac_f32_e32 v22, v34, v20
	v_fmac_f32_e32 v23, v35, v20
	v_fma_f32 v20, v36, v20, v49
	v_fmac_f32_e32 v63, v37, v21
	v_fmac_f32_e32 v70, v39, v21
	v_fmac_f32_e32 v71, v41, v21
	v_fmac_f32_e32 v72, v42, v21
	v_fmac_f32_e32 v28, v43, v21
	v_fmac_f32_e32 v29, v44, v21
	v_fmac_f32_e32 v26, v30, v21
	v_fmac_f32_e32 v27, v32, v21
	v_fmac_f32_e32 v24, v9, v21
	v_fmac_f32_e32 v25, v31, v21
	v_fmac_f32_e32 v22, v33, v21
	v_fmac_f32_e32 v23, v34, v21
	v_fmac_f32_e32 v20, v35, v21
	v_fma_f32 v21, v36, v21, v49
	v_fmac_f32_e32 v63, v40, v18
	v_fmac_f32_e32 v70, v37, v18
	v_fmac_f32_e32 v71, v39, v18
	v_fmac_f32_e32 v72, v41, v18
	v_fmac_f32_e32 v28, v42, v18
	v_fmac_f32_e32 v29, v43, v18
	v_fmac_f32_e32 v26, v44, v18
	v_fmac_f32_e32 v27, v30, v18
	v_fmac_f32_e32 v24, v32, v18
	v_fmac_f32_e32 v25, v9, v18
	v_fmac_f32_e32 v22, v31, v18
	v_fmac_f32_e32 v23, v33, v18
	v_fmac_f32_e32 v20, v34, v18
	v_fmac_f32_e32 v21, v35, v18
	v_fma_f32 v18, v36, v18, v49
	v_fmac_f32_e32 v63, v38, v19
	v_fmac_f32_e32 v70, v40, v19
	v_fmac_f32_e32 v71, v37, v19
	v_fmac_f32_e32 v72, v39, v19
	v_fmac_f32_e32 v28, v41, v19
	v_fmac_f32_e32 v29, v42, v19
	v_fmac_f32_e32 v26, v43, v19
	v_fmac_f32_e32 v27, v44, v19
	v_fmac_f32_e32 v24, v30, v19
	v_fmac_f32_e32 v25, v32, v19
	v_fmac_f32_e32 v22, v9, v19
	v_fmac_f32_e32 v23, v31, v19
	v_fmac_f32_e32 v20, v33, v19
	v_fmac_f32_e32 v21, v34, v19
	v_fmac_f32_e32 v18, v35, v19
	v_fma_f32 v19, v36, v19, v49
	v_fmac_f32_e32 v63, v53, v16
	v_fmac_f32_e32 v70, v38, v16
	v_fmac_f32_e32 v71, v40, v16
	v_fmac_f32_e32 v72, v37, v16
	v_fmac_f32_e32 v28, v39, v16
	v_fmac_f32_e32 v29, v41, v16
	v_fmac_f32_e32 v26, v42, v16
	v_fmac_f32_e32 v27, v43, v16
	v_fmac_f32_e32 v24, v44, v16
	v_fmac_f32_e32 v25, v30, v16
	v_fmac_f32_e32 v22, v32, v16
	v_fmac_f32_e32 v23, v9, v16
	v_fmac_f32_e32 v20, v31, v16
	v_fmac_f32_e32 v21, v33, v16
	v_fmac_f32_e32 v18, v34, v16
	v_fmac_f32_e32 v19, v35, v16
	v_fma_f32 v16, v36, v16, v49
	v_fmac_f32_e32 v63, v60, v17
	v_fmac_f32_e32 v70, v53, v17
	v_fmac_f32_e32 v71, v38, v17
	v_fmac_f32_e32 v72, v40, v17
	v_fmac_f32_e32 v28, v37, v17
	v_fmac_f32_e32 v29, v39, v17
	v_fmac_f32_e32 v26, v41, v17
	v_fmac_f32_e32 v27, v42, v17
	v_fmac_f32_e32 v24, v43, v17
	v_fmac_f32_e32 v25, v44, v17
	v_fmac_f32_e32 v22, v30, v17
	v_fmac_f32_e32 v23, v32, v17
	v_fmac_f32_e32 v20, v9, v17
	v_fmac_f32_e32 v21, v31, v17
	v_fmac_f32_e32 v18, v33, v17
	v_fmac_f32_e32 v19, v34, v17
	v_fmac_f32_e32 v16, v35, v17
	v_fma_f32 v17, v36, v17, v49
	v_fmac_f32_e32 v63, v52, v14
	v_fmac_f32_e32 v70, v60, v14
	v_fmac_f32_e32 v71, v53, v14
	v_fmac_f32_e32 v72, v38, v14
	v_fmac_f32_e32 v28, v40, v14
	v_fmac_f32_e32 v29, v37, v14
	v_fmac_f32_e32 v26, v39, v14
	v_fmac_f32_e32 v27, v41, v14
	v_fmac_f32_e32 v24, v42, v14
	v_fmac_f32_e32 v25, v43, v14
	v_fmac_f32_e32 v22, v44, v14
	v_fmac_f32_e32 v23, v30, v14
	v_fmac_f32_e32 v20, v32, v14
	v_fmac_f32_e32 v21, v9, v14
	v_fmac_f32_e32 v18, v31, v14
	v_fmac_f32_e32 v19, v33, v14
	v_fmac_f32_e32 v16, v34, v14
; __device__ __forceinline__ void conv_phase(LAS unsigned char* lds, const bf16_t* PROJ, const float* cw, const float* cb, const float* lg, const float* lb, bf16_t* MIXIN, int G, int tid) {
;     ...
;             for (int o = 0; o < 8; ++o) { float acc = bias;
; #pragma unroll
;                 for (int k = 0; k < 31; ++k) acc += w[k] * win[o + k];
;                 y[8 * blk + o] = acc; } }
	v_fmac_f32_e32 v17, v35, v14
	v_fma_f32 v14, v36, v14, v49
	v_fmac_f32_e32 v63, v51, v15
	v_fmac_f32_e32 v70, v52, v15
	v_fmac_f32_e32 v71, v60, v15
	v_fmac_f32_e32 v72, v53, v15
	v_fmac_f32_e32 v28, v38, v15
	v_fmac_f32_e32 v29, v40, v15
	v_fmac_f32_e32 v26, v37, v15
	v_fmac_f32_e32 v27, v39, v15
	v_fmac_f32_e32 v24, v41, v15
	v_fmac_f32_e32 v25, v42, v15
	v_fmac_f32_e32 v22, v43, v15
	v_fmac_f32_e32 v23, v44, v15
	v_fmac_f32_e32 v20, v30, v15
	v_fmac_f32_e32 v21, v32, v15
	v_fmac_f32_e32 v18, v9, v15
	v_fmac_f32_e32 v19, v31, v15
	v_fmac_f32_e32 v16, v33, v15
	v_fmac_f32_e32 v17, v34, v15
	v_fmac_f32_e32 v14, v35, v15
	v_fma_f32 v15, v36, v15, v49
	v_fmac_f32_e32 v63, v50, v12
	v_fmac_f32_e32 v70, v51, v12
	v_fmac_f32_e32 v71, v52, v12
	v_fmac_f32_e32 v72, v60, v12
	v_fmac_f32_e32 v28, v53, v12
	v_fmac_f32_e32 v29, v38, v12
	v_fmac_f32_e32 v26, v40, v12
	v_fmac_f32_e32 v27, v37, v12
	v_fmac_f32_e32 v24, v39, v12
	v_fmac_f32_e32 v25, v41, v12
	v_fmac_f32_e32 v22, v42, v12
	v_fmac_f32_e32 v23, v43, v12
	v_fmac_f32_e32 v20, v44, v12
	v_fmac_f32_e32 v21, v30, v12
	v_fmac_f32_e32 v18, v32, v12
	v_fmac_f32_e32 v19, v9, v12
	v_fmac_f32_e32 v16, v31, v12
	v_fmac_f32_e32 v17, v33, v12
	v_fmac_f32_e32 v14, v34, v12
	v_fmac_f32_e32 v15, v35, v12
	v_fma_f32 v12, v36, v12, v49
	v_fmac_f32_e32 v63, v59, v13
	v_fmac_f32_e32 v70, v50, v13
	v_fmac_f32_e32 v71, v51, v13
	v_fmac_f32_e32 v72, v52, v13
	v_fmac_f32_e32 v28, v60, v13
	v_fmac_f32_e32 v29, v53, v13
	v_fmac_f32_e32 v26, v38, v13
	v_fmac_f32_e32 v27, v40, v13
	v_fmac_f32_e32 v24, v37, v13
	v_fmac_f32_e32 v25, v39, v13
	v_fmac_f32_e32 v22, v41, v13
	v_fmac_f32_e32 v23, v42, v13
	v_fmac_f32_e32 v20, v43, v13
	v_fmac_f32_e32 v21, v44, v13
	v_fmac_f32_e32 v18, v30, v13
	v_fmac_f32_e32 v19, v32, v13
	v_fmac_f32_e32 v16, v9, v13
	v_fmac_f32_e32 v17, v31, v13
	v_fmac_f32_e32 v14, v33, v13
	v_fmac_f32_e32 v15, v34, v13
	v_fmac_f32_e32 v12, v35, v13
	v_fma_f32 v13, v36, v13, v49
	v_fmac_f32_e32 v63, v47, v10
	v_fmac_f32_e32 v70, v59, v10
	v_fmac_f32_e32 v71, v50, v10
	v_fmac_f32_e32 v72, v51, v10
	v_fmac_f32_e32 v28, v52, v10
	v_fmac_f32_e32 v29, v60, v10
	v_fmac_f32_e32 v26, v53, v10
	v_fmac_f32_e32 v27, v38, v10
	v_fmac_f32_e32 v24, v40, v10
	v_fmac_f32_e32 v25, v37, v10
	v_fmac_f32_e32 v22, v39, v10
	v_fmac_f32_e32 v23, v41, v10
	v_fmac_f32_e32 v20, v42, v10
	v_fmac_f32_e32 v21, v43, v10
	v_fmac_f32_e32 v18, v44, v10
	v_fmac_f32_e32 v19, v30, v10
	v_fmac_f32_e32 v16, v32, v10
	v_fmac_f32_e32 v17, v9, v10
	v_fmac_f32_e32 v14, v31, v10
	v_fmac_f32_e32 v15, v33, v10
	v_fmac_f32_e32 v12, v34, v10
	v_fmac_f32_e32 v13, v35, v10
	v_fma_f32 v10, v36, v10, v49
	v_fmac_f32_e32 v63, v46, v11
	v_fmac_f32_e32 v70, v47, v11
	v_fmac_f32_e32 v71, v59, v11
	v_fmac_f32_e32 v72, v50, v11
	v_fmac_f32_e32 v28, v51, v11
	v_fmac_f32_e32 v29, v52, v11
	v_fmac_f32_e32 v26, v60, v11
	v_fmac_f32_e32 v27, v53, v11
	v_fmac_f32_e32 v24, v38, v11
	v_fmac_f32_e32 v25, v40, v11
	v_fmac_f32_e32 v22, v37, v11
	v_fmac_f32_e32 v23, v39, v11
	v_fmac_f32_e32 v20, v41, v11
	v_fmac_f32_e32 v21, v42, v11
	v_fmac_f32_e32 v18, v43, v11
	v_fmac_f32_e32 v19, v44, v11
	v_fmac_f32_e32 v16, v30, v11
	v_fmac_f32_e32 v17, v32, v11
	v_fmac_f32_e32 v14, v9, v11
	v_fmac_f32_e32 v15, v31, v11
	v_fmac_f32_e32 v12, v33, v11
	v_fmac_f32_e32 v13, v34, v11
	v_fmac_f32_e32 v10, v35, v11
	v_fma_f32 v11, v36, v11, v49
	v_fmac_f32_e32 v63, v48, v6
	v_fmac_f32_e32 v70, v46, v6
	v_fmac_f32_e32 v71, v47, v6
	v_fmac_f32_e32 v72, v59, v6
	v_fmac_f32_e32 v28, v50, v6
	v_fmac_f32_e32 v29, v51, v6
	v_fmac_f32_e32 v26, v52, v6
	v_fmac_f32_e32 v27, v60, v6
	v_fmac_f32_e32 v24, v53, v6
	v_fmac_f32_e32 v25, v38, v6
	v_fmac_f32_e32 v22, v40, v6
	v_fmac_f32_e32 v23, v37, v6
	v_fmac_f32_e32 v20, v39, v6
	v_fmac_f32_e32 v21, v41, v6
	v_fmac_f32_e32 v18, v42, v6
	v_fmac_f32_e32 v19, v43, v6
	v_fmac_f32_e32 v16, v44, v6
	v_fmac_f32_e32 v17, v30, v6
	v_fmac_f32_e32 v14, v32, v6
	v_fmac_f32_e32 v15, v9, v6
	v_fmac_f32_e32 v12, v31, v6
	v_fmac_f32_e32 v13, v33, v6
	v_fmac_f32_e32 v10, v34, v6
	v_fmac_f32_e32 v11, v35, v6
	v_fma_f32 v6, v36, v6, v49
	v_fmac_f32_e32 v63, v56, v7
	v_fmac_f32_e32 v70, v48, v7
	v_fmac_f32_e32 v71, v46, v7
	v_fmac_f32_e32 v72, v47, v7
	v_fmac_f32_e32 v28, v59, v7
	v_fmac_f32_e32 v29, v50, v7
	v_fmac_f32_e32 v26, v51, v7
	v_fmac_f32_e32 v27, v52, v7
	v_fmac_f32_e32 v24, v60, v7
	v_fmac_f32_e32 v25, v53, v7
	v_fmac_f32_e32 v22, v38, v7
	v_fmac_f32_e32 v23, v40, v7
	v_fmac_f32_e32 v20, v37, v7
	v_fmac_f32_e32 v21, v39, v7
	v_fmac_f32_e32 v18, v41, v7
	v_fmac_f32_e32 v19, v42, v7
	v_fmac_f32_e32 v16, v43, v7
	v_fmac_f32_e32 v17, v44, v7
	v_fmac_f32_e32 v14, v30, v7
	v_fmac_f32_e32 v15, v32, v7
	v_fmac_f32_e32 v12, v9, v7
	v_fmac_f32_e32 v13, v31, v7
	v_fmac_f32_e32 v10, v33, v7
	v_fmac_f32_e32 v11, v34, v7
	v_fmac_f32_e32 v6, v35, v7
	v_fma_f32 v7, v36, v7, v49
	v_fmac_f32_e32 v63, v45, v4
	v_fmac_f32_e32 v70, v56, v4
	v_fmac_f32_e32 v71, v48, v4
	v_fmac_f32_e32 v72, v46, v4
	v_fmac_f32_e32 v28, v47, v4
	v_fmac_f32_e32 v29, v59, v4
	v_fmac_f32_e32 v26, v50, v4
	v_fmac_f32_e32 v27, v51, v4
	v_fmac_f32_e32 v24, v52, v4
	v_fmac_f32_e32 v25, v60, v4
	v_fmac_f32_e32 v22, v53, v4
	v_fmac_f32_e32 v23, v38, v4
	v_fmac_f32_e32 v20, v40, v4
	v_fmac_f32_e32 v21, v37, v4
	v_fmac_f32_e32 v18, v39, v4
	v_fmac_f32_e32 v19, v41, v4
	v_fmac_f32_e32 v16, v42, v4
	v_fmac_f32_e32 v17, v43, v4
	v_fmac_f32_e32 v14, v44, v4
	v_fmac_f32_e32 v15, v30, v4
	v_fmac_f32_e32 v12, v32, v4
	v_fmac_f32_e32 v13, v9, v4
	v_fmac_f32_e32 v10, v31, v4
	v_fmac_f32_e32 v11, v33, v4
	v_fmac_f32_e32 v6, v34, v4
	v_fmac_f32_e32 v7, v35, v4
	v_fma_f32 v4, v36, v4, v49
	v_fmac_f32_e32 v63, v58, v5
; __device__ __forceinline__ void conv_phase(LAS unsigned char* lds, const bf16_t* PROJ, const float* cw, const float* cb, const float* lg, const float* lb, bf16_t* MIXIN, int G, int tid) {
;     ...
;         for (int blk = 0; blk < 4; ++blk) { float win[38];
; #pragma unroll
;             for (int x = 0; x < 38; ++x) win[x] = U[(8 * blk + x) * 512 + c];
; #pragma unroll
;             for (int o = 0; o < 8; ++o) { float acc = bias;
; #pragma unroll
;                 for (int k = 0; k < 31; ++k) acc += w[k] * win[o + k];
;                 y[8 * blk + o] = acc; } }
	v_fmac_f32_e32 v70, v45, v5
	v_fmac_f32_e32 v71, v56, v5
	v_fmac_f32_e32 v72, v48, v5
	v_fmac_f32_e32 v28, v46, v5
	v_fmac_f32_e32 v29, v47, v5
	v_fmac_f32_e32 v26, v59, v5
	v_fmac_f32_e32 v27, v50, v5
	v_fmac_f32_e32 v24, v51, v5
	v_fmac_f32_e32 v25, v52, v5
	v_fmac_f32_e32 v22, v60, v5
	v_fmac_f32_e32 v23, v53, v5
	v_fmac_f32_e32 v20, v38, v5
	v_fmac_f32_e32 v21, v40, v5
	v_fmac_f32_e32 v18, v37, v5
	v_fmac_f32_e32 v19, v39, v5
	v_fmac_f32_e32 v16, v41, v5
	v_fmac_f32_e32 v17, v42, v5
	v_fmac_f32_e32 v14, v43, v5
	v_fmac_f32_e32 v15, v44, v5
	v_fmac_f32_e32 v12, v30, v5
	v_fmac_f32_e32 v13, v32, v5
	v_fmac_f32_e32 v10, v9, v5
	v_fmac_f32_e32 v11, v31, v5
	v_fmac_f32_e32 v6, v33, v5
	v_fmac_f32_e32 v7, v34, v5
	v_fmac_f32_e32 v4, v35, v5
	v_fma_f32 v5, v36, v5, v49
	v_fmac_f32_e32 v63, v57, v2
	v_fmac_f32_e32 v70, v58, v2
	v_fmac_f32_e32 v71, v45, v2
	v_fmac_f32_e32 v72, v56, v2
	v_fmac_f32_e32 v28, v48, v2
	v_fmac_f32_e32 v29, v46, v2
	v_fmac_f32_e32 v26, v47, v2
	v_fmac_f32_e32 v27, v59, v2
	v_fmac_f32_e32 v24, v50, v2
	v_fmac_f32_e32 v25, v51, v2
	v_fmac_f32_e32 v22, v52, v2
	v_fmac_f32_e32 v23, v60, v2
	v_fmac_f32_e32 v20, v53, v2
	v_fmac_f32_e32 v21, v38, v2
	v_fmac_f32_e32 v18, v40, v2
	v_fmac_f32_e32 v19, v37, v2
	v_fmac_f32_e32 v16, v39, v2
	v_fmac_f32_e32 v17, v41, v2
	v_fmac_f32_e32 v14, v42, v2
	v_fmac_f32_e32 v15, v43, v2
	v_fmac_f32_e32 v12, v44, v2
	v_fmac_f32_e32 v13, v30, v2
	v_fmac_f32_e32 v10, v32, v2
	v_fmac_f32_e32 v11, v9, v2
	v_fmac_f32_e32 v6, v31, v2
	v_fmac_f32_e32 v7, v33, v2
	v_fmac_f32_e32 v4, v34, v2
	v_fmac_f32_e32 v5, v35, v2
	v_fma_f32 v2, v36, v2, v49
	v_fmac_f32_e32 v63, v54, v3
	v_fmac_f32_e32 v70, v57, v3
	v_fmac_f32_e32 v71, v58, v3
	v_fmac_f32_e32 v72, v45, v3
	v_fmac_f32_e32 v28, v56, v3
	v_fmac_f32_e32 v29, v48, v3
	v_fmac_f32_e32 v26, v46, v3
	v_fmac_f32_e32 v27, v47, v3
	v_fmac_f32_e32 v24, v59, v3
	v_fmac_f32_e32 v25, v50, v3
	v_fmac_f32_e32 v22, v51, v3
	v_fmac_f32_e32 v23, v52, v3
	v_fmac_f32_e32 v20, v60, v3
	v_fmac_f32_e32 v21, v53, v3
	v_fmac_f32_e32 v18, v38, v3
	v_fmac_f32_e32 v19, v40, v3
	v_fmac_f32_e32 v16, v37, v3
	v_fmac_f32_e32 v17, v39, v3
	v_fmac_f32_e32 v14, v41, v3
	v_fmac_f32_e32 v15, v42, v3
	v_fmac_f32_e32 v12, v43, v3
	v_fmac_f32_e32 v13, v44, v3
	v_fmac_f32_e32 v10, v30, v3
	v_fmac_f32_e32 v11, v32, v3
	v_fmac_f32_e32 v6, v9, v3
	v_fmac_f32_e32 v7, v31, v3
	v_fmac_f32_e32 v4, v33, v3
	v_fmac_f32_e32 v5, v34, v3
	v_fmac_f32_e32 v2, v35, v3
	v_fma_f32 v3, v36, v3, v49
	v_fmac_f32_e32 v63, v55, v0
	v_fmac_f32_e32 v70, v54, v0
	v_fmac_f32_e32 v71, v57, v0
	v_fmac_f32_e32 v72, v58, v0
	v_fmac_f32_e32 v28, v45, v0
	v_fmac_f32_e32 v29, v56, v0
	v_fmac_f32_e32 v26, v48, v0
	v_fmac_f32_e32 v27, v46, v0
	v_fmac_f32_e32 v24, v47, v0
	v_fmac_f32_e32 v25, v59, v0
	v_fmac_f32_e32 v22, v50, v0
	v_fmac_f32_e32 v23, v51, v0
	v_fmac_f32_e32 v20, v52, v0
	v_fmac_f32_e32 v21, v60, v0
	v_fmac_f32_e32 v18, v53, v0
	v_fmac_f32_e32 v19, v38, v0
	v_fmac_f32_e32 v16, v40, v0
	v_fmac_f32_e32 v17, v37, v0
	v_fmac_f32_e32 v14, v39, v0
	v_fmac_f32_e32 v15, v41, v0
	v_fmac_f32_e32 v12, v42, v0
	v_fmac_f32_e32 v13, v43, v0
	v_fmac_f32_e32 v10, v44, v0
	v_fmac_f32_e32 v11, v30, v0
	v_fmac_f32_e32 v6, v32, v0
	v_fmac_f32_e32 v7, v9, v0
	v_fmac_f32_e32 v4, v31, v0
	v_fmac_f32_e32 v5, v33, v0
	v_fmac_f32_e32 v2, v34, v0
	v_fmac_f32_e32 v3, v35, v0
	v_fma_f32 v0, v36, v0, v49
	v_fmac_f32_e32 v0, v35, v1
	v_fmac_f32_e32 v49, v36, v1
	v_add_u32_e32 v73, 0x13000, v62
	v_fmac_f32_e32 v0, v34, v64
	v_fmac_f32_e32 v49, v35, v64
	ds_read_b32 v73, v73
	v_fmac_f32_e32 v3, v34, v1
	v_fmac_f32_e32 v0, v33, v65
	v_fmac_f32_e32 v49, v34, v65
	v_fmac_f32_e32 v2, v33, v1
	v_fmac_f32_e32 v3, v33, v64
	v_fmac_f32_e32 v0, v31, v66
	v_fmac_f32_e32 v49, v33, v66
	v_fmac_f32_e32 v5, v31, v1
	v_fmac_f32_e32 v2, v31, v64
	v_fmac_f32_e32 v3, v31, v65
	s_waitcnt lgkmcnt(12)
	v_fmac_f32_e32 v0, v9, v67
	v_fmac_f32_e32 v49, v31, v67
	v_fmac_f32_e32 v4, v9, v1
	v_fmac_f32_e32 v5, v9, v64
	v_fmac_f32_e32 v2, v9, v65
	v_fmac_f32_e32 v3, v9, v66
	s_waitcnt lgkmcnt(8)
	v_fmac_f32_e32 v0, v32, v68
	v_fmac_f32_e32 v49, v9, v68
	v_add_u32_e32 v80, 0x16800, v62
	v_add_u32_e32 v87, 0x1a000, v62
	v_add_u32_e32 v94, 0x1d800, v62
	v_fmac_f32_e32 v7, v32, v1
	v_fmac_f32_e32 v4, v32, v64
	v_fmac_f32_e32 v5, v32, v65
	v_fmac_f32_e32 v2, v32, v66
	v_fmac_f32_e32 v3, v32, v67
	s_waitcnt lgkmcnt(4)
	v_fmac_f32_e32 v0, v30, v69
	v_fmac_f32_e32 v49, v32, v69
	ds_read_b32 v80, v80
	ds_read_b32 v87, v87
	ds_read_b32 v94, v94
	v_fmac_f32_e32 v6, v30, v1
	v_fmac_f32_e32 v7, v30, v64
	v_fmac_f32_e32 v4, v30, v65
	v_fmac_f32_e32 v5, v30, v66
	v_fmac_f32_e32 v2, v30, v67
	v_fmac_f32_e32 v3, v30, v68
	s_waitcnt lgkmcnt(3)
; __device__ __forceinline__ void conv_phase(LAS unsigned char* lds, const bf16_t* PROJ, const float* cw, const float* cb, const float* lg, const float* lb, bf16_t* MIXIN, int G, int tid) {
;     ...
;             for (int o = 0; o < 8; ++o) { float acc = bias;
; #pragma unroll
;                 for (int k = 0; k < 31; ++k) acc += w[k] * win[o + k];
;                 y[8 * blk + o] = acc; } }
	v_fmac_f32_e32 v0, v44, v73
	v_fmac_f32_e32 v49, v30, v73
	v_fmac_f32_e32 v11, v44, v1
	v_fmac_f32_e32 v6, v44, v64
	v_fmac_f32_e32 v7, v44, v65
	v_fmac_f32_e32 v4, v44, v66
	v_fmac_f32_e32 v5, v44, v67
	v_fmac_f32_e32 v2, v44, v68
	v_fmac_f32_e32 v3, v44, v69
	v_fmac_f32_e32 v0, v43, v74
	v_fmac_f32_e32 v49, v44, v74
	v_fmac_f32_e32 v10, v43, v1
	v_fmac_f32_e32 v11, v43, v64
	v_fmac_f32_e32 v6, v43, v65
	v_fmac_f32_e32 v7, v43, v66
	v_fmac_f32_e32 v4, v43, v67
	v_fmac_f32_e32 v5, v43, v68
	v_fmac_f32_e32 v2, v43, v69
	v_fmac_f32_e32 v3, v43, v73
	v_fmac_f32_e32 v0, v42, v75
	v_fmac_f32_e32 v49, v43, v75
	v_fmac_f32_e32 v13, v42, v1
	v_fmac_f32_e32 v10, v42, v64
	v_fmac_f32_e32 v11, v42, v65
	v_fmac_f32_e32 v6, v42, v66
	v_fmac_f32_e32 v7, v42, v67
	v_fmac_f32_e32 v4, v42, v68
	v_fmac_f32_e32 v5, v42, v69
	v_fmac_f32_e32 v2, v42, v73
	v_fmac_f32_e32 v3, v42, v74
	v_fmac_f32_e32 v0, v41, v76
	v_fmac_f32_e32 v49, v42, v76
	v_fmac_f32_e32 v12, v41, v1
	v_fmac_f32_e32 v13, v41, v64
	v_fmac_f32_e32 v10, v41, v65
	v_fmac_f32_e32 v11, v41, v66
	v_fmac_f32_e32 v6, v41, v67
	v_fmac_f32_e32 v7, v41, v68
	v_fmac_f32_e32 v4, v41, v69
	v_fmac_f32_e32 v5, v41, v73
	v_fmac_f32_e32 v2, v41, v74
	v_fmac_f32_e32 v3, v41, v75
	v_fmac_f32_e32 v0, v39, v77
	v_fmac_f32_e32 v49, v41, v77
	v_fmac_f32_e32 v15, v39, v1
	v_fmac_f32_e32 v12, v39, v64
	v_fmac_f32_e32 v13, v39, v65
	v_fmac_f32_e32 v10, v39, v66
	v_fmac_f32_e32 v11, v39, v67
	v_fmac_f32_e32 v6, v39, v68
	v_fmac_f32_e32 v7, v39, v69
	v_fmac_f32_e32 v4, v39, v73
	v_fmac_f32_e32 v5, v39, v74
	v_fmac_f32_e32 v2, v39, v75
	v_fmac_f32_e32 v3, v39, v76
	v_fmac_f32_e32 v0, v37, v78
	v_fmac_f32_e32 v49, v39, v78
	v_fmac_f32_e32 v14, v37, v1
	v_fmac_f32_e32 v15, v37, v64
	v_fmac_f32_e32 v12, v37, v65
	v_fmac_f32_e32 v13, v37, v66
	v_fmac_f32_e32 v10, v37, v67
	v_fmac_f32_e32 v11, v37, v68
	v_fmac_f32_e32 v6, v37, v69
	v_fmac_f32_e32 v7, v37, v73
	v_fmac_f32_e32 v4, v37, v74
	v_fmac_f32_e32 v5, v37, v75
	v_fmac_f32_e32 v2, v37, v76
	v_fmac_f32_e32 v3, v37, v77
	v_fmac_f32_e32 v0, v40, v79
	v_fmac_f32_e32 v49, v37, v79
	v_fmac_f32_e32 v17, v40, v1
	v_fmac_f32_e32 v14, v40, v64
	v_fmac_f32_e32 v15, v40, v65
	v_fmac_f32_e32 v12, v40, v66
	v_fmac_f32_e32 v13, v40, v67
	v_fmac_f32_e32 v10, v40, v68
	v_fmac_f32_e32 v11, v40, v69
	v_fmac_f32_e32 v6, v40, v73
	v_fmac_f32_e32 v7, v40, v74
	v_fmac_f32_e32 v4, v40, v75
	v_fmac_f32_e32 v5, v40, v76
	v_fmac_f32_e32 v2, v40, v77
	v_fmac_f32_e32 v3, v40, v78
	s_waitcnt lgkmcnt(2)
	v_fmac_f32_e32 v0, v38, v80
	v_fmac_f32_e32 v49, v40, v80
	v_fmac_f32_e32 v16, v38, v1
	v_fmac_f32_e32 v17, v38, v64
	v_fmac_f32_e32 v14, v38, v65
	v_fmac_f32_e32 v15, v38, v66
	v_fmac_f32_e32 v12, v38, v67
	v_fmac_f32_e32 v13, v38, v68
	v_fmac_f32_e32 v10, v38, v69
	v_fmac_f32_e32 v11, v38, v73
	v_fmac_f32_e32 v6, v38, v74
	v_fmac_f32_e32 v7, v38, v75
	v_fmac_f32_e32 v4, v38, v76
	v_fmac_f32_e32 v5, v38, v77
	v_fmac_f32_e32 v2, v38, v78
	v_fmac_f32_e32 v3, v38, v79
	v_fmac_f32_e32 v0, v53, v81
	v_fmac_f32_e32 v49, v38, v81
	v_fmac_f32_e32 v19, v53, v1
	v_fmac_f32_e32 v16, v53, v64
	v_fmac_f32_e32 v17, v53, v65
	v_fmac_f32_e32 v14, v53, v66
	v_fmac_f32_e32 v15, v53, v67
	v_fmac_f32_e32 v12, v53, v68
	v_fmac_f32_e32 v13, v53, v69
	v_fmac_f32_e32 v10, v53, v73
	v_fmac_f32_e32 v11, v53, v74
	v_fmac_f32_e32 v6, v53, v75
	v_fmac_f32_e32 v7, v53, v76
	v_fmac_f32_e32 v4, v53, v77
	v_fmac_f32_e32 v5, v53, v78
	v_fmac_f32_e32 v2, v53, v79
	v_fmac_f32_e32 v3, v53, v80
	v_fmac_f32_e32 v0, v60, v82
	v_fmac_f32_e32 v49, v53, v82
	v_fmac_f32_e32 v18, v60, v1
	v_fmac_f32_e32 v19, v60, v64
	v_fmac_f32_e32 v16, v60, v65
	v_fmac_f32_e32 v17, v60, v66
	v_fmac_f32_e32 v14, v60, v67
	v_fmac_f32_e32 v15, v60, v68
	v_fmac_f32_e32 v12, v60, v69
	v_fmac_f32_e32 v13, v60, v73
	v_fmac_f32_e32 v10, v60, v74
	v_fmac_f32_e32 v11, v60, v75
	v_fmac_f32_e32 v6, v60, v76
	v_fmac_f32_e32 v7, v60, v77
	v_fmac_f32_e32 v4, v60, v78
	v_fmac_f32_e32 v5, v60, v79
	v_fmac_f32_e32 v2, v60, v80
	v_fmac_f32_e32 v3, v60, v81
	v_fmac_f32_e32 v0, v52, v83
	v_fmac_f32_e32 v49, v60, v83
	v_fmac_f32_e32 v21, v52, v1
	v_fmac_f32_e32 v18, v52, v64
	v_fmac_f32_e32 v19, v52, v65
	v_fmac_f32_e32 v16, v52, v66
	v_fmac_f32_e32 v17, v52, v67
	v_fmac_f32_e32 v14, v52, v68
	v_fmac_f32_e32 v15, v52, v69
	v_fmac_f32_e32 v12, v52, v73
	v_fmac_f32_e32 v13, v52, v74
	v_fmac_f32_e32 v10, v52, v75
	v_fmac_f32_e32 v11, v52, v76
	v_fmac_f32_e32 v6, v52, v77
	v_fmac_f32_e32 v7, v52, v78
	v_fmac_f32_e32 v4, v52, v79
	v_fmac_f32_e32 v5, v52, v80
	v_fmac_f32_e32 v2, v52, v81
	v_fmac_f32_e32 v3, v52, v82
	v_fmac_f32_e32 v0, v51, v84
	v_fmac_f32_e32 v49, v52, v84
	v_fmac_f32_e32 v20, v51, v1
	v_fmac_f32_e32 v21, v51, v64
	v_fmac_f32_e32 v18, v51, v65
	v_fmac_f32_e32 v19, v51, v66
	v_fmac_f32_e32 v16, v51, v67
	v_fmac_f32_e32 v17, v51, v68
	v_fmac_f32_e32 v14, v51, v69
	v_fmac_f32_e32 v15, v51, v73
	v_fmac_f32_e32 v12, v51, v74
	v_fmac_f32_e32 v13, v51, v75
	v_fmac_f32_e32 v10, v51, v76
	v_fmac_f32_e32 v11, v51, v77
	v_fmac_f32_e32 v6, v51, v78
	v_fmac_f32_e32 v7, v51, v79
	v_fmac_f32_e32 v4, v51, v80
	v_fmac_f32_e32 v5, v51, v81
	v_fmac_f32_e32 v2, v51, v82
	v_fmac_f32_e32 v3, v51, v83
	v_fmac_f32_e32 v0, v50, v85
	v_fmac_f32_e32 v49, v51, v85
	v_fmac_f32_e32 v23, v50, v1
	v_fmac_f32_e32 v20, v50, v64
	v_fmac_f32_e32 v21, v50, v65
	v_fmac_f32_e32 v18, v50, v66
	v_fmac_f32_e32 v19, v50, v67
	v_fmac_f32_e32 v16, v50, v68
	v_fmac_f32_e32 v17, v50, v69
	v_fmac_f32_e32 v14, v50, v73
	v_fmac_f32_e32 v15, v50, v74
	v_fmac_f32_e32 v12, v50, v75
	v_fmac_f32_e32 v13, v50, v76
	v_fmac_f32_e32 v10, v50, v77
	v_fmac_f32_e32 v11, v50, v78
	v_fmac_f32_e32 v6, v50, v79
	v_fmac_f32_e32 v7, v50, v80
	v_fmac_f32_e32 v4, v50, v81
	v_fmac_f32_e32 v5, v50, v82
	v_fmac_f32_e32 v2, v50, v83
	v_fmac_f32_e32 v3, v50, v84
	v_fmac_f32_e32 v0, v59, v86
	v_fmac_f32_e32 v49, v50, v86
	v_fmac_f32_e32 v22, v59, v1
	v_fmac_f32_e32 v23, v59, v64
	v_fmac_f32_e32 v20, v59, v65
	v_fmac_f32_e32 v21, v59, v66
	v_fmac_f32_e32 v18, v59, v67
	v_fmac_f32_e32 v19, v59, v68
	v_fmac_f32_e32 v16, v59, v69
	v_fmac_f32_e32 v17, v59, v73
	v_fmac_f32_e32 v14, v59, v74
	v_fmac_f32_e32 v15, v59, v75
	v_fmac_f32_e32 v12, v59, v76
	v_fmac_f32_e32 v13, v59, v77
	v_fmac_f32_e32 v10, v59, v78
	v_fmac_f32_e32 v11, v59, v79
	v_fmac_f32_e32 v6, v59, v80
	v_fmac_f32_e32 v7, v59, v81
	v_fmac_f32_e32 v4, v59, v82
	v_fmac_f32_e32 v5, v59, v83
	v_fmac_f32_e32 v2, v59, v84
	v_fmac_f32_e32 v3, v59, v85
	s_waitcnt lgkmcnt(1)
; __device__ __forceinline__ void conv_phase(LAS unsigned char* lds, const bf16_t* PROJ, const float* cw, const float* cb, const float* lg, const float* lb, bf16_t* MIXIN, int G, int tid) {
;     ...
;             for (int o = 0; o < 8; ++o) { float acc = bias;
; #pragma unroll
;                 for (int k = 0; k < 31; ++k) acc += w[k] * win[o + k];
;                 y[8 * blk + o] = acc; } }
	v_fmac_f32_e32 v0, v47, v87
	v_fmac_f32_e32 v49, v59, v87
	v_fmac_f32_e32 v25, v47, v1
	v_fmac_f32_e32 v22, v47, v64
	v_fmac_f32_e32 v23, v47, v65
	v_fmac_f32_e32 v20, v47, v66
	v_fmac_f32_e32 v21, v47, v67
	v_fmac_f32_e32 v18, v47, v68
	v_fmac_f32_e32 v19, v47, v69
	v_fmac_f32_e32 v16, v47, v73
	v_fmac_f32_e32 v17, v47, v74
	v_fmac_f32_e32 v14, v47, v75
	v_fmac_f32_e32 v15, v47, v76
	v_fmac_f32_e32 v12, v47, v77
	v_fmac_f32_e32 v13, v47, v78
	v_fmac_f32_e32 v10, v47, v79
	v_fmac_f32_e32 v11, v47, v80
	v_fmac_f32_e32 v6, v47, v81
	v_fmac_f32_e32 v7, v47, v82
	v_fmac_f32_e32 v4, v47, v83
	v_fmac_f32_e32 v5, v47, v84
	v_fmac_f32_e32 v2, v47, v85
	v_fmac_f32_e32 v3, v47, v86
	v_fmac_f32_e32 v0, v46, v88
	v_fmac_f32_e32 v49, v47, v88
	v_fmac_f32_e32 v24, v46, v1
	v_fmac_f32_e32 v25, v46, v64
	v_fmac_f32_e32 v22, v46, v65
	v_fmac_f32_e32 v23, v46, v66
	v_fmac_f32_e32 v20, v46, v67
	v_fmac_f32_e32 v21, v46, v68
	v_fmac_f32_e32 v18, v46, v69
	v_fmac_f32_e32 v19, v46, v73
	v_fmac_f32_e32 v16, v46, v74
	v_fmac_f32_e32 v17, v46, v75
	v_fmac_f32_e32 v14, v46, v76
	v_fmac_f32_e32 v15, v46, v77
	v_fmac_f32_e32 v12, v46, v78
	v_fmac_f32_e32 v13, v46, v79
	v_fmac_f32_e32 v10, v46, v80
	v_fmac_f32_e32 v11, v46, v81
	v_fmac_f32_e32 v6, v46, v82
	v_fmac_f32_e32 v7, v46, v83
	v_fmac_f32_e32 v4, v46, v84
	v_fmac_f32_e32 v5, v46, v85
	v_fmac_f32_e32 v2, v46, v86
	v_fmac_f32_e32 v3, v46, v87
	v_fmac_f32_e32 v0, v48, v89
	v_fmac_f32_e32 v49, v46, v89
	v_fmac_f32_e32 v27, v48, v1
	v_fmac_f32_e32 v24, v48, v64
	v_fmac_f32_e32 v25, v48, v65
	v_fmac_f32_e32 v22, v48, v66
	v_fmac_f32_e32 v23, v48, v67
	v_fmac_f32_e32 v20, v48, v68
	v_fmac_f32_e32 v21, v48, v69
	v_fmac_f32_e32 v18, v48, v73
	v_fmac_f32_e32 v19, v48, v74
	v_fmac_f32_e32 v16, v48, v75
	v_fmac_f32_e32 v17, v48, v76
	v_fmac_f32_e32 v14, v48, v77
	v_fmac_f32_e32 v15, v48, v78
	v_fmac_f32_e32 v12, v48, v79
	v_fmac_f32_e32 v13, v48, v80
	v_fmac_f32_e32 v10, v48, v81
	v_fmac_f32_e32 v11, v48, v82
	v_fmac_f32_e32 v6, v48, v83
	v_fmac_f32_e32 v7, v48, v84
	v_fmac_f32_e32 v4, v48, v85
	v_fmac_f32_e32 v5, v48, v86
	v_fmac_f32_e32 v2, v48, v87
	v_fmac_f32_e32 v3, v48, v88
	v_fmac_f32_e32 v0, v56, v90
	v_fmac_f32_e32 v49, v48, v90
	v_fmac_f32_e32 v26, v56, v1
	v_fmac_f32_e32 v27, v56, v64
	v_fmac_f32_e32 v24, v56, v65
	v_fmac_f32_e32 v25, v56, v66
	v_fmac_f32_e32 v22, v56, v67
	v_fmac_f32_e32 v23, v56, v68
	v_fmac_f32_e32 v20, v56, v69
	v_fmac_f32_e32 v21, v56, v73
	v_fmac_f32_e32 v18, v56, v74
	v_fmac_f32_e32 v19, v56, v75
	v_fmac_f32_e32 v16, v56, v76
	v_fmac_f32_e32 v17, v56, v77
	v_fmac_f32_e32 v14, v56, v78
	v_fmac_f32_e32 v15, v56, v79
	v_fmac_f32_e32 v12, v56, v80
	v_fmac_f32_e32 v13, v56, v81
	v_fmac_f32_e32 v10, v56, v82
	v_fmac_f32_e32 v11, v56, v83
	v_fmac_f32_e32 v6, v56, v84
	v_fmac_f32_e32 v7, v56, v85
	v_fmac_f32_e32 v4, v56, v86
	v_fmac_f32_e32 v5, v56, v87
	v_fmac_f32_e32 v2, v56, v88
	v_fmac_f32_e32 v3, v56, v89
	v_fmac_f32_e32 v0, v45, v91
	v_fmac_f32_e32 v49, v56, v91
	v_fmac_f32_e32 v29, v45, v1
	v_fmac_f32_e32 v26, v45, v64
	v_fmac_f32_e32 v27, v45, v65
	v_fmac_f32_e32 v24, v45, v66
	v_fmac_f32_e32 v25, v45, v67
	v_fmac_f32_e32 v22, v45, v68
	v_fmac_f32_e32 v23, v45, v69
	v_fmac_f32_e32 v20, v45, v73
	v_fmac_f32_e32 v21, v45, v74
	v_fmac_f32_e32 v18, v45, v75
	v_fmac_f32_e32 v19, v45, v76
	v_fmac_f32_e32 v16, v45, v77
	v_fmac_f32_e32 v17, v45, v78
	v_fmac_f32_e32 v14, v45, v79
	v_fmac_f32_e32 v15, v45, v80
	v_fmac_f32_e32 v12, v45, v81
	v_fmac_f32_e32 v13, v45, v82
	v_fmac_f32_e32 v10, v45, v83
	v_fmac_f32_e32 v11, v45, v84
	v_fmac_f32_e32 v6, v45, v85
	v_fmac_f32_e32 v7, v45, v86
	v_fmac_f32_e32 v4, v45, v87
	v_fmac_f32_e32 v5, v45, v88
	v_fmac_f32_e32 v2, v45, v89
	v_fmac_f32_e32 v3, v45, v90
	v_fmac_f32_e32 v0, v58, v92
	v_fmac_f32_e32 v49, v45, v92
	v_fmac_f32_e32 v28, v58, v1
	v_fmac_f32_e32 v29, v58, v64
	v_fmac_f32_e32 v26, v58, v65
	v_fmac_f32_e32 v27, v58, v66
	v_fmac_f32_e32 v24, v58, v67
	v_fmac_f32_e32 v25, v58, v68
	v_fmac_f32_e32 v22, v58, v69
	v_fmac_f32_e32 v23, v58, v73
	v_fmac_f32_e32 v20, v58, v74
	v_fmac_f32_e32 v21, v58, v75
	v_fmac_f32_e32 v18, v58, v76
	v_fmac_f32_e32 v19, v58, v77
	v_fmac_f32_e32 v16, v58, v78
	v_fmac_f32_e32 v17, v58, v79
	v_fmac_f32_e32 v14, v58, v80
	v_fmac_f32_e32 v15, v58, v81
	v_fmac_f32_e32 v12, v58, v82
	v_fmac_f32_e32 v13, v58, v83
	v_fmac_f32_e32 v10, v58, v84
	v_fmac_f32_e32 v11, v58, v85
	v_fmac_f32_e32 v6, v58, v86
	v_fmac_f32_e32 v7, v58, v87
	v_fmac_f32_e32 v4, v58, v88
	v_fmac_f32_e32 v5, v58, v89
	v_fmac_f32_e32 v2, v58, v90
	v_fmac_f32_e32 v3, v58, v91
	v_fmac_f32_e32 v0, v57, v93
	v_fmac_f32_e32 v49, v58, v93
	v_fmac_f32_e32 v72, v57, v1
	v_fmac_f32_e32 v28, v57, v64
	v_fmac_f32_e32 v29, v57, v65
	v_fmac_f32_e32 v26, v57, v66
	v_fmac_f32_e32 v27, v57, v67
	v_fmac_f32_e32 v24, v57, v68
	v_fmac_f32_e32 v25, v57, v69
	v_fmac_f32_e32 v22, v57, v73
	v_fmac_f32_e32 v23, v57, v74
	v_fmac_f32_e32 v20, v57, v75
	v_fmac_f32_e32 v21, v57, v76
	v_fmac_f32_e32 v18, v57, v77
	v_fmac_f32_e32 v19, v57, v78
	v_fmac_f32_e32 v16, v57, v79
	v_fmac_f32_e32 v17, v57, v80
	v_fmac_f32_e32 v14, v57, v81
	v_fmac_f32_e32 v15, v57, v82
	v_fmac_f32_e32 v12, v57, v83
	v_fmac_f32_e32 v13, v57, v84
	v_fmac_f32_e32 v10, v57, v85
	v_fmac_f32_e32 v11, v57, v86
	v_fmac_f32_e32 v6, v57, v87
	v_fmac_f32_e32 v7, v57, v88
	v_fmac_f32_e32 v4, v57, v89
	v_fmac_f32_e32 v5, v57, v90
	v_fmac_f32_e32 v2, v57, v91
	v_fmac_f32_e32 v3, v57, v92
	s_waitcnt lgkmcnt(0)
; #define LAS __attribute__((address_space(3)))
; __device__ __forceinline__ void conv_phase(LAS unsigned char* lds, const bf16_t* PROJ, const float* cw, const float* cb, const float* lg, const float* lb, bf16_t* MIXIN, int G, int tid) {
;     ...
;             for (int o = 0; o < 8; ++o) { float acc = bias;
; #pragma unroll
;                 for (int k = 0; k < 31; ++k) acc += w[k] * win[o + k];
;                 y[8 * blk + o] = acc; } }
;         __syncthreads();
; #pragma unroll
;         for (int tt = 0; tt < 32; ++tt) U[tt * 512 + c] = y[tt];
;         __syncthreads();
; #pragma unroll
;         for (int q = 0; q < 4; ++q) { const int tt = 4 * wave + q;
;             f32x4 a = *(const LAS f32x4*)(U + tt * 512 + 8 * lane), b = *(const LAS f32x4*)(U + tt * 512 + 8 * lane + 4);
;             const float mean = wave_sum((a[0] + a[1]) + (a[2] + a[3]) + (b[0] + b[1]) + (b[2] + b[3])) * (1.f / 512.f);
;             a = a - mean; b = b - mean;
;             const float var = wave_sum((a[0] * a[0] + a[1] * a[1]) + (a[2] * a[2] + a[3] * a[3]) + (b[0] * b[0] + b[1] * b[1]) + (b[2] * b[2] + b[3] * b[3])) * (1.f / 512.f);
	v_fmac_f32_e32 v0, v54, v94
	v_fmac_f32_e32 v49, v57, v94
	v_fmac_f32_e32 v70, v55, v1
	v_fmac_f32_e32 v71, v54, v1
	v_fmac_f32_e32 v72, v54, v64
	v_fmac_f32_e32 v28, v54, v65
	v_fmac_f32_e32 v29, v54, v66
	v_fmac_f32_e32 v26, v54, v67
	v_fmac_f32_e32 v27, v54, v68
	v_fmac_f32_e32 v24, v54, v69
	v_fmac_f32_e32 v25, v54, v73
	v_fmac_f32_e32 v22, v54, v74
	v_fmac_f32_e32 v23, v54, v75
	v_fmac_f32_e32 v20, v54, v76
	v_fmac_f32_e32 v21, v54, v77
	v_fmac_f32_e32 v18, v54, v78
	v_fmac_f32_e32 v19, v54, v79
	v_fmac_f32_e32 v16, v54, v80
	v_fmac_f32_e32 v17, v54, v81
	v_fmac_f32_e32 v14, v54, v82
	v_fmac_f32_e32 v15, v54, v83
	v_fmac_f32_e32 v12, v54, v84
	v_fmac_f32_e32 v13, v54, v85
	v_fmac_f32_e32 v10, v54, v86
	v_fmac_f32_e32 v11, v54, v87
	v_fmac_f32_e32 v6, v54, v88
	v_fmac_f32_e32 v7, v54, v89
	v_fmac_f32_e32 v4, v54, v90
	v_fmac_f32_e32 v5, v54, v91
	v_fmac_f32_e32 v2, v54, v92
	v_fmac_f32_e32 v3, v54, v93
	v_fmac_f32_e32 v0, v55, v95
	v_fmac_f32_e32 v49, v54, v95
	v_fmac_f32_e32 v71, v55, v64
	v_fmac_f32_e32 v72, v55, v65
	v_fmac_f32_e32 v28, v55, v66
	v_fmac_f32_e32 v29, v55, v67
	v_fmac_f32_e32 v26, v55, v68
	v_fmac_f32_e32 v27, v55, v69
	v_fmac_f32_e32 v24, v55, v73
	v_fmac_f32_e32 v25, v55, v74
	v_fmac_f32_e32 v22, v55, v75
	v_fmac_f32_e32 v23, v55, v76
	v_fmac_f32_e32 v20, v55, v77
	v_fmac_f32_e32 v21, v55, v78
	v_fmac_f32_e32 v18, v55, v79
	v_fmac_f32_e32 v19, v55, v80
	v_fmac_f32_e32 v16, v55, v81
	v_fmac_f32_e32 v17, v55, v82
	v_fmac_f32_e32 v14, v55, v83
	v_fmac_f32_e32 v15, v55, v84
	v_fmac_f32_e32 v12, v55, v85
	v_fmac_f32_e32 v13, v55, v86
	v_fmac_f32_e32 v10, v55, v87
	v_fmac_f32_e32 v11, v55, v88
	v_fmac_f32_e32 v6, v55, v89
	v_fmac_f32_e32 v7, v55, v90
	v_fmac_f32_e32 v4, v55, v91
	v_fmac_f32_e32 v5, v55, v92
	v_fmac_f32_e32 v2, v55, v93
	v_fmac_f32_e32 v3, v55, v94
	v_fmac_f32_e32 v49, v55, v96
	s_barrier
	ds_write2st64_b32 v62, v63, v70 offset1:8
	ds_write2st64_b32 v62, v71, v72 offset0:16 offset1:24
	ds_write2st64_b32 v62, v28, v29 offset0:32 offset1:40
	ds_write2st64_b32 v62, v26, v27 offset0:48 offset1:56
	ds_write2st64_b32 v62, v24, v25 offset0:64 offset1:72
	ds_write2st64_b32 v62, v22, v23 offset0:80 offset1:88
	ds_write2st64_b32 v62, v20, v21 offset0:96 offset1:104
	ds_write2st64_b32 v62, v18, v19 offset0:112 offset1:120
	ds_write2st64_b32 v62, v16, v17 offset0:128 offset1:136
	ds_write2st64_b32 v62, v14, v15 offset0:144 offset1:152
	ds_write2st64_b32 v62, v12, v13 offset0:160 offset1:168
	ds_write2st64_b32 v62, v10, v11 offset0:176 offset1:184
	ds_write2st64_b32 v62, v6, v7 offset0:192 offset1:200
	ds_write2st64_b32 v62, v4, v5 offset0:208 offset1:216
	ds_write2st64_b32 v62, v2, v3 offset0:224 offset1:232
	ds_write2st64_b32 v62, v0, v49 offset0:240 offset1:248
	v_and_b32_e32 v0, 64, v230
	v_add_u32_e32 v0, 64, v0
	v_xor_b32_e32 v1, 1, v230
	v_cmp_lt_i32_e32 vcc, v1, v0
	s_lshl_b32 s5, s4, 2
	s_lshl_b32 s4, s4, 13
	v_cndmask_b32_e32 v1, v230, v1, vcc
	v_lshlrev_b32_e32 v13, 2, v1
	v_xor_b32_e32 v1, 2, v230
	v_cmp_lt_i32_e32 vcc, v1, v0
	v_lshlrev_b32_e32 v9, 2, v61
	s_add_i32 s4, s4, 0
	v_cndmask_b32_e32 v1, v230, v1, vcc
	v_lshlrev_b32_e32 v18, 2, v1
	v_xor_b32_e32 v1, 4, v230
	v_cmp_lt_i32_e32 vcc, v1, v0
	v_add_u32_e32 v23, s4, v9
	s_waitcnt lgkmcnt(0)
	v_cndmask_b32_e32 v1, v230, v1, vcc
	v_lshlrev_b32_e32 v19, 2, v1
	v_xor_b32_e32 v1, 8, v230
	v_cmp_lt_i32_e32 vcc, v1, v0
	s_barrier
	s_nop 0
	v_cndmask_b32_e32 v1, v230, v1, vcc
	v_lshlrev_b32_e32 v20, 2, v1
	v_xor_b32_e32 v1, 16, v230
	v_cmp_lt_i32_e32 vcc, v1, v0
	v_readlane_b32 s18, v250, 10
	s_add_i32 s4, s6, s5
	v_cndmask_b32_e32 v1, v230, v1, vcc
	v_lshlrev_b32_e32 v21, 2, v1
	v_xor_b32_e32 v1, 32, v230
	v_cmp_lt_i32_e32 vcc, v1, v0
	v_lshlrev_b32_e32 v164, 1, v61
	v_readlane_b32 s19, v250, 11
	v_cndmask_b32_e32 v0, v230, v1, vcc
	v_lshlrev_b32_e32 v22, 2, v0
	ds_read_b128 v[4:7], v23
	ds_read_b128 v[0:3], v23 offset:16
	s_ashr_i32 s5, s4, 31
	v_lshl_add_u64 v[10:11], s[18:19], 0, v[164:165]
	s_lshl_b64 s[18:19], s[4:5], 11
	s_waitcnt lgkmcnt(1)
	v_mov_b32_e32 v14, v5
	v_mov_b32_e32 v15, v6
	v_mov_b32_e32 v16, v4
	v_mov_b32_e32 v17, v7
	v_pk_add_f32 v[14:15], v[14:15], v[16:17]
	s_waitcnt lgkmcnt(0)
	v_mov_b32_e32 v16, v2
	v_mov_b32_e32 v17, v0
	v_mov_b32_e32 v24, v3
	v_mov_b32_e32 v25, v1
	v_pk_add_f32 v[16:17], v[16:17], v[24:25]
	v_add_f32_e32 v12, v14, v15
	v_add_f32_e32 v12, v12, v17
	v_add_f32_e32 v12, v16, v12
	ds_bpermute_b32 v14, v13, v12
	s_add_i32 s7, s7, s50
	s_waitcnt lgkmcnt(0)
	v_add_f32_e32 v12, v12, v14
	ds_bpermute_b32 v14, v18, v12
	s_waitcnt lgkmcnt(0)
	v_add_f32_e32 v12, v12, v14
	ds_bpermute_b32 v14, v19, v12
	s_waitcnt lgkmcnt(0)
	v_add_f32_e32 v12, v12, v14
	ds_bpermute_b32 v14, v20, v12
	s_waitcnt lgkmcnt(0)
	v_add_f32_e32 v12, v12, v14
	ds_bpermute_b32 v14, v21, v12
	s_waitcnt lgkmcnt(0)
	v_add_f32_e32 v12, v12, v14
	ds_bpermute_b32 v14, v22, v12
	s_waitcnt lgkmcnt(0)
	v_add_f32_e32 v12, v12, v14
	v_fmamk_f32 v5, v12, 0xbb000000, v5
	v_fmamk_f32 v4, v12, 0xbb000000, v4
	v_fmamk_f32 v7, v12, 0xbb000000, v7
	v_fmac_f32_e32 v6, 0xbb000000, v12
	v_pk_mul_f32 v[14:15], v[6:7], v[6:7]
	v_pk_mul_f32 v[16:17], v[4:5], v[4:5]
	v_fmamk_f32 v1, v12, 0xbb000000, v1
	v_fmamk_f32 v0, v12, 0xbb000000, v0
	v_fmamk_f32 v3, v12, 0xbb000000, v3
	v_fmac_f32_e32 v2, 0xbb000000, v12
	v_pk_mov_b32 v[24:25], v[16:17], v[14:15] op_sel:[1,0]
	v_mov_b32_e32 v17, v15
	v_pk_add_f32 v[14:15], v[24:25], v[16:17]
	v_pk_mul_f32 v[16:17], v[2:3], v[2:3]
	v_pk_mul_f32 v[24:25], v[0:1], v[0:1]
	v_mov_b32_e32 v26, v16
	v_mov_b32_e32 v27, v24
	v_mov_b32_e32 v24, v17
	v_pk_add_f32 v[16:17], v[26:27], v[24:25]
	v_add_f32_e32 v12, v14, v15
	v_add_f32_e32 v12, v17, v12
	v_add_f32_e32 v12, v16, v12
	ds_bpermute_b32 v14, v13, v12
	s_waitcnt lgkmcnt(0)
; __device__ __forceinline__ u32x4 pack8(const f32x4 v0, const f32x4 v1) { u32x4 w; w.x = cvt_pk_bf16(v0[0], v0[1]); w.y = cvt_pk_bf16(v0[2], v0[3]); w.z = cvt_pk_bf16(v1[0], v1[1]); w.w = cvt_pk_bf16(v1[2], v1[3]); return w; }
; __device__ __forceinline__ float silu_fast(float x) { return x * __builtin_amdgcn_rcpf(1.f + __expf(-x)); }
; #define LAS __attribute__((address_space(3)))
; __device__ __forceinline__ void conv_phase(LAS unsigned char* lds, const bf16_t* PROJ, const float* cw, const float* cb, const float* lg, const float* lb, bf16_t* MIXIN, int G, int tid) {
;     ...
;         for (int q = 0; q < 4; ++q) { const int tt = 4 * wave + q;
;             f32x4 a = *(const LAS f32x4*)(U + tt * 512 + 8 * lane), b = *(const LAS f32x4*)(U + tt * 512 + 8 * lane + 4);
;             const float mean = wave_sum((a[0] + a[1]) + (a[2] + a[3]) + (b[0] + b[1]) + (b[2] + b[3])) * (1.f / 512.f);
;             a = a - mean; b = b - mean;
;             const float var = wave_sum((a[0] * a[0] + a[1] * a[1]) + (a[2] * a[2] + a[3] * a[3]) + (b[0] * b[0] + b[1] * b[1]) + (b[2] * b[2] + b[3] * b[3])) * (1.f / 512.f);
;             const float rstd = rsqrtf(var + LN_EPS);
;             a = a * rstd * *(const f32x4*)(lg + 8 * lane) + *(const f32x4*)(lb + 8 * lane); b = b * rstd * *(const f32x4*)(lg + 8 * lane + 4) + *(const f32x4*)(lb + 8 * lane + 4);
; #pragma unroll
;             for (int x = 0; x < 4; ++x) { a[x] = pg8::silu_fast(a[x]); b[x] = pg8::silu_fast(b[x]); }
;             *(u32x4*)(MIXIN + (size_t)(row0 + tt) * D + 8 * lane) = pg8::pack8(a, b); }
	v_add_f32_e32 v12, v12, v14
	ds_bpermute_b32 v14, v18, v12
	s_waitcnt lgkmcnt(0)
	v_add_f32_e32 v12, v12, v14
	ds_bpermute_b32 v14, v19, v12
	s_waitcnt lgkmcnt(0)
	v_add_f32_e32 v12, v12, v14
	ds_bpermute_b32 v14, v20, v12
	s_waitcnt lgkmcnt(0)
	v_add_f32_e32 v12, v12, v14
	ds_bpermute_b32 v14, v21, v12
	s_waitcnt lgkmcnt(0)
	v_add_f32_e32 v12, v12, v14
	ds_bpermute_b32 v14, v22, v12
	s_waitcnt lgkmcnt(0)
	v_add_f32_e32 v12, v12, v14
	v_fmamk_f32 v12, v12, 0x3b000000, v173
	v_cmp_gt_f32_e32 vcc, s81, v12
	v_mul_f32_e32 v14, 0x4b800000, v12
	s_nop 0
	v_cndmask_b32_e32 v12, v12, v14, vcc
	v_rsq_f32_e32 v12, v12
	s_nop 0
	v_mul_f32_e32 v14, 0x45800000, v12
	v_cndmask_b32_e32 v12, v12, v14, vcc
	v_pk_mul_f32 v[14:15], v[4:5], v[12:13] op_sel_hi:[1,0]
	v_pk_mul_f32 v[16:17], v[6:7], v[12:13] op_sel_hi:[1,0]
	v_pk_mul_f32 v[0:1], v[0:1], v[12:13] op_sel_hi:[1,0]
	v_pk_mul_f32 v[2:3], v[2:3], v[12:13] op_sel_hi:[1,0]
	v_pk_fma_f32 v[0:1], v[100:101], v[0:1], v[108:109]
	v_pk_fma_f32 v[2:3], v[102:103], v[2:3], v[110:111]
	v_mul_f32_e32 v5, 0xbfb8aa3b, v0
	v_mul_f32_e32 v6, 0xbfb8aa3b, v1
	v_mul_f32_e32 v7, 0xbfb8aa3b, v2
	v_exp_f32_e32 v5, v5
	v_exp_f32_e32 v6, v6
	v_exp_f32_e32 v7, v7
	v_pk_fma_f32 v[16:17], v[106:107], v[16:17], v[114:115]
	v_add_f32_e32 v5, 1.0, v5
	v_add_f32_e32 v6, 1.0, v6
	v_add_f32_e32 v7, 1.0, v7
	v_rcp_f32_e32 v5, v5
	v_rcp_f32_e32 v6, v6
	v_rcp_f32_e32 v7, v7
	v_pk_fma_f32 v[14:15], v[104:105], v[14:15], v[112:113]
	v_mul_f32_e32 v5, v0, v5
	v_mul_f32_e32 v4, 0xbfb8aa3b, v14
	v_mul_f32_e32 v0, 0xbfb8aa3b, v15
	v_mul_f32_e32 v6, v1, v6
	v_mul_f32_e32 v1, 0xbfb8aa3b, v16
	v_mul_f32_e32 v7, v2, v7
	v_mul_f32_e32 v2, 0xbfb8aa3b, v17
	v_exp_f32_e32 v4, v4
	v_exp_f32_e32 v0, v0
	v_exp_f32_e32 v1, v1
	v_exp_f32_e32 v2, v2
	v_mul_f32_e32 v12, 0xbfb8aa3b, v3
	v_exp_f32_e32 v12, v12
	v_add_f32_e32 v4, 1.0, v4
	v_add_f32_e32 v0, 1.0, v0
	v_add_f32_e32 v1, 1.0, v1
	v_add_f32_e32 v2, 1.0, v2
	v_rcp_f32_e32 v4, v4
	v_rcp_f32_e32 v0, v0
	v_rcp_f32_e32 v1, v1
	v_rcp_f32_e32 v2, v2
	v_add_f32_e32 v12, 1.0, v12
	v_rcp_f32_e32 v12, v12
	v_mul_f32_e32 v4, v14, v4
	v_mul_f32_e32 v0, v15, v0
	v_mul_f32_e32 v1, v16, v1
	v_mul_f32_e32 v2, v17, v2
	v_mul_f32_e32 v3, v3, v12
	v_cvt_pk_bf16_f32 v0, v4, v0
	v_cvt_pk_bf16_f32 v1, v1, v2
	v_cvt_pk_bf16_f32 v2, v5, v6
	v_lshl_add_u64 v[4:5], v[10:11], 0, s[18:19]
	v_cvt_pk_bf16_f32 v3, v7, v3
	global_store_dwordx4 v[4:5], v[0:3], off
	ds_read_b128 v[4:7], v23 offset:2048
	ds_read_b128 v[0:3], v23 offset:2064
	s_add_i32 s18, s4, 1
	s_ashr_i32 s19, s18, 31
	s_lshl_b64 s[18:19], s[18:19], 11
	s_waitcnt lgkmcnt(1)
	v_mov_b32_e32 v14, v5
	v_mov_b32_e32 v15, v6
	v_mov_b32_e32 v16, v4
	v_mov_b32_e32 v17, v7
	v_pk_add_f32 v[14:15], v[14:15], v[16:17]
	s_waitcnt lgkmcnt(0)
	v_mov_b32_e32 v16, v2
	v_mov_b32_e32 v17, v0
	v_mov_b32_e32 v24, v3
	v_mov_b32_e32 v25, v1
	v_pk_add_f32 v[16:17], v[16:17], v[24:25]
	v_add_f32_e32 v12, v14, v15
	v_add_f32_e32 v12, v12, v17
	v_add_f32_e32 v12, v16, v12
	ds_bpermute_b32 v14, v13, v12
	s_waitcnt lgkmcnt(0)
	v_add_f32_e32 v12, v12, v14
	ds_bpermute_b32 v14, v18, v12
	s_waitcnt lgkmcnt(0)
	v_add_f32_e32 v12, v12, v14
	ds_bpermute_b32 v14, v19, v12
	s_waitcnt lgkmcnt(0)
	v_add_f32_e32 v12, v12, v14
	ds_bpermute_b32 v14, v20, v12
	s_waitcnt lgkmcnt(0)
	v_add_f32_e32 v12, v12, v14
	ds_bpermute_b32 v14, v21, v12
	s_waitcnt lgkmcnt(0)
	v_add_f32_e32 v12, v12, v14
	ds_bpermute_b32 v14, v22, v12
	s_waitcnt lgkmcnt(0)
	v_add_f32_e32 v12, v12, v14
	v_fmamk_f32 v5, v12, 0xbb000000, v5
	v_fmamk_f32 v4, v12, 0xbb000000, v4
	v_fmamk_f32 v7, v12, 0xbb000000, v7
	v_fmac_f32_e32 v6, 0xbb000000, v12
	v_pk_mul_f32 v[14:15], v[6:7], v[6:7]
	v_pk_mul_f32 v[16:17], v[4:5], v[4:5]
	v_fmamk_f32 v1, v12, 0xbb000000, v1
	v_fmamk_f32 v0, v12, 0xbb000000, v0
	v_fmamk_f32 v3, v12, 0xbb000000, v3
	v_fmac_f32_e32 v2, 0xbb000000, v12
	v_pk_mov_b32 v[24:25], v[16:17], v[14:15] op_sel:[1,0]
	v_mov_b32_e32 v17, v15
	v_pk_add_f32 v[14:15], v[24:25], v[16:17]
	v_pk_mul_f32 v[16:17], v[2:3], v[2:3]
	v_pk_mul_f32 v[24:25], v[0:1], v[0:1]
	v_mov_b32_e32 v26, v16
	v_mov_b32_e32 v27, v24
	v_mov_b32_e32 v24, v17
	v_pk_add_f32 v[16:17], v[26:27], v[24:25]
	v_add_f32_e32 v12, v14, v15
	v_add_f32_e32 v12, v17, v12
	v_add_f32_e32 v12, v16, v12
	ds_bpermute_b32 v14, v13, v12
	s_waitcnt lgkmcnt(0)
	v_add_f32_e32 v12, v12, v14
	ds_bpermute_b32 v14, v18, v12
	s_waitcnt lgkmcnt(0)
	v_add_f32_e32 v12, v12, v14
	ds_bpermute_b32 v14, v19, v12
	s_waitcnt lgkmcnt(0)
	v_add_f32_e32 v12, v12, v14
	ds_bpermute_b32 v14, v20, v12
	s_waitcnt lgkmcnt(0)
	v_add_f32_e32 v12, v12, v14
	ds_bpermute_b32 v14, v21, v12
	s_waitcnt lgkmcnt(0)
	v_add_f32_e32 v12, v12, v14
	ds_bpermute_b32 v14, v22, v12
	s_waitcnt lgkmcnt(0)
; __device__ __forceinline__ u32x4 pack8(const f32x4 v0, const f32x4 v1) { u32x4 w; w.x = cvt_pk_bf16(v0[0], v0[1]); w.y = cvt_pk_bf16(v0[2], v0[3]); w.z = cvt_pk_bf16(v1[0], v1[1]); w.w = cvt_pk_bf16(v1[2], v1[3]); return w; }
; __device__ __forceinline__ float silu_fast(float x) { return x * __builtin_amdgcn_rcpf(1.f + __expf(-x)); }
; #define LAS __attribute__((address_space(3)))
; __device__ __forceinline__ void conv_phase(LAS unsigned char* lds, const bf16_t* PROJ, const float* cw, const float* cb, const float* lg, const float* lb, bf16_t* MIXIN, int G, int tid) {
;     ...
;         for (int q = 0; q < 4; ++q) { const int tt = 4 * wave + q;
;             f32x4 a = *(const LAS f32x4*)(U + tt * 512 + 8 * lane), b = *(const LAS f32x4*)(U + tt * 512 + 8 * lane + 4);
;             const float mean = wave_sum((a[0] + a[1]) + (a[2] + a[3]) + (b[0] + b[1]) + (b[2] + b[3])) * (1.f / 512.f);
;             a = a - mean; b = b - mean;
;             const float var = wave_sum((a[0] * a[0] + a[1] * a[1]) + (a[2] * a[2] + a[3] * a[3]) + (b[0] * b[0] + b[1] * b[1]) + (b[2] * b[2] + b[3] * b[3])) * (1.f / 512.f);
;             const float rstd = rsqrtf(var + LN_EPS);
;             a = a * rstd * *(const f32x4*)(lg + 8 * lane) + *(const f32x4*)(lb + 8 * lane); b = b * rstd * *(const f32x4*)(lg + 8 * lane + 4) + *(const f32x4*)(lb + 8 * lane + 4);
; #pragma unroll
;             for (int x = 0; x < 4; ++x) { a[x] = pg8::silu_fast(a[x]); b[x] = pg8::silu_fast(b[x]); }
;             *(u32x4*)(MIXIN + (size_t)(row0 + tt) * D + 8 * lane) = pg8::pack8(a, b); }
	v_add_f32_e32 v12, v12, v14
	v_fmamk_f32 v12, v12, 0x3b000000, v173
	v_cmp_gt_f32_e32 vcc, s81, v12
	v_mul_f32_e32 v14, 0x4b800000, v12
	s_nop 0
	v_cndmask_b32_e32 v12, v12, v14, vcc
	v_rsq_f32_e32 v12, v12
	s_nop 0
	v_mul_f32_e32 v14, 0x45800000, v12
	v_cndmask_b32_e32 v12, v12, v14, vcc
	v_pk_mul_f32 v[14:15], v[4:5], v[12:13] op_sel_hi:[1,0]
	v_pk_mul_f32 v[16:17], v[6:7], v[12:13] op_sel_hi:[1,0]
	v_pk_mul_f32 v[0:1], v[0:1], v[12:13] op_sel_hi:[1,0]
	v_pk_mul_f32 v[2:3], v[2:3], v[12:13] op_sel_hi:[1,0]
	v_pk_fma_f32 v[0:1], v[100:101], v[0:1], v[108:109]
	v_pk_fma_f32 v[2:3], v[102:103], v[2:3], v[110:111]
	v_mul_f32_e32 v5, 0xbfb8aa3b, v0
	v_mul_f32_e32 v6, 0xbfb8aa3b, v1
	v_mul_f32_e32 v7, 0xbfb8aa3b, v2
	v_exp_f32_e32 v5, v5
	v_exp_f32_e32 v6, v6
	v_exp_f32_e32 v7, v7
	v_pk_fma_f32 v[16:17], v[106:107], v[16:17], v[114:115]
	v_add_f32_e32 v5, 1.0, v5
	v_add_f32_e32 v6, 1.0, v6
	v_add_f32_e32 v7, 1.0, v7
	v_rcp_f32_e32 v5, v5
	v_rcp_f32_e32 v6, v6
	v_rcp_f32_e32 v7, v7
	v_pk_fma_f32 v[14:15], v[104:105], v[14:15], v[112:113]
	v_mul_f32_e32 v5, v0, v5
	v_mul_f32_e32 v4, 0xbfb8aa3b, v14
	v_mul_f32_e32 v0, 0xbfb8aa3b, v15
	v_mul_f32_e32 v6, v1, v6
	v_mul_f32_e32 v1, 0xbfb8aa3b, v16
	v_mul_f32_e32 v7, v2, v7
	v_mul_f32_e32 v2, 0xbfb8aa3b, v17
	v_exp_f32_e32 v4, v4
	v_exp_f32_e32 v0, v0
	v_exp_f32_e32 v1, v1
	v_exp_f32_e32 v2, v2
	v_mul_f32_e32 v12, 0xbfb8aa3b, v3
	v_exp_f32_e32 v12, v12
	v_add_f32_e32 v4, 1.0, v4
	v_add_f32_e32 v0, 1.0, v0
	v_add_f32_e32 v1, 1.0, v1
	v_add_f32_e32 v2, 1.0, v2
	v_rcp_f32_e32 v4, v4
	v_rcp_f32_e32 v0, v0
	v_rcp_f32_e32 v1, v1
	v_rcp_f32_e32 v2, v2
	v_add_f32_e32 v12, 1.0, v12
	v_rcp_f32_e32 v12, v12
	v_mul_f32_e32 v4, v14, v4
	v_mul_f32_e32 v0, v15, v0
	v_mul_f32_e32 v1, v16, v1
	v_mul_f32_e32 v2, v17, v2
	v_mul_f32_e32 v3, v3, v12
	v_cvt_pk_bf16_f32 v0, v4, v0
	v_cvt_pk_bf16_f32 v1, v1, v2
	v_cvt_pk_bf16_f32 v2, v5, v6
	v_lshl_add_u64 v[4:5], v[10:11], 0, s[18:19]
	v_cvt_pk_bf16_f32 v3, v7, v3
	global_store_dwordx4 v[4:5], v[0:3], off
	ds_read_b128 v[4:7], v23 offset:4096
	ds_read_b128 v[0:3], v23 offset:4112
	s_add_i32 s18, s4, 2
	s_ashr_i32 s19, s18, 31
	s_lshl_b64 s[18:19], s[18:19], 11
	s_waitcnt lgkmcnt(1)
	v_mov_b32_e32 v14, v5
	v_mov_b32_e32 v15, v6
	v_mov_b32_e32 v16, v4
	v_mov_b32_e32 v17, v7
	v_pk_add_f32 v[14:15], v[14:15], v[16:17]
	s_waitcnt lgkmcnt(0)
	v_mov_b32_e32 v16, v2
	v_mov_b32_e32 v17, v0
	v_mov_b32_e32 v24, v3
	v_mov_b32_e32 v25, v1
	v_pk_add_f32 v[16:17], v[16:17], v[24:25]
	v_add_f32_e32 v12, v14, v15
	v_add_f32_e32 v12, v12, v17
	v_add_f32_e32 v12, v16, v12
	ds_bpermute_b32 v14, v13, v12
	s_add_i32 s4, s4, 3
	s_ashr_i32 s5, s4, 31
	s_lshl_b64 s[4:5], s[4:5], 11
	s_waitcnt lgkmcnt(0)
	v_add_f32_e32 v12, v12, v14
	ds_bpermute_b32 v14, v18, v12
	s_waitcnt lgkmcnt(0)
	v_add_f32_e32 v12, v12, v14
	ds_bpermute_b32 v14, v19, v12
	s_waitcnt lgkmcnt(0)
	v_add_f32_e32 v12, v12, v14
	ds_bpermute_b32 v14, v20, v12
	s_waitcnt lgkmcnt(0)
	v_add_f32_e32 v12, v12, v14
	ds_bpermute_b32 v14, v21, v12
	s_waitcnt lgkmcnt(0)
	v_add_f32_e32 v12, v12, v14
	ds_bpermute_b32 v14, v22, v12
	s_waitcnt lgkmcnt(0)
	v_add_f32_e32 v12, v12, v14
	v_fmamk_f32 v5, v12, 0xbb000000, v5
	v_fmamk_f32 v4, v12, 0xbb000000, v4
	v_fmamk_f32 v7, v12, 0xbb000000, v7
	v_fmac_f32_e32 v6, 0xbb000000, v12
	v_pk_mul_f32 v[14:15], v[6:7], v[6:7]
	v_pk_mul_f32 v[16:17], v[4:5], v[4:5]
	v_fmamk_f32 v1, v12, 0xbb000000, v1
	v_fmamk_f32 v0, v12, 0xbb000000, v0
	v_fmamk_f32 v3, v12, 0xbb000000, v3
	v_fmac_f32_e32 v2, 0xbb000000, v12
	v_pk_mov_b32 v[24:25], v[16:17], v[14:15] op_sel:[1,0]
	v_mov_b32_e32 v17, v15
	v_pk_add_f32 v[14:15], v[24:25], v[16:17]
	v_pk_mul_f32 v[16:17], v[2:3], v[2:3]
	v_pk_mul_f32 v[24:25], v[0:1], v[0:1]
	v_mov_b32_e32 v26, v16
	v_mov_b32_e32 v27, v24
	v_mov_b32_e32 v24, v17
	v_pk_add_f32 v[16:17], v[26:27], v[24:25]
	v_add_f32_e32 v12, v14, v15
	v_add_f32_e32 v12, v17, v12
	v_add_f32_e32 v12, v16, v12
	ds_bpermute_b32 v14, v13, v12
	s_waitcnt lgkmcnt(0)
	v_add_f32_e32 v12, v12, v14
	ds_bpermute_b32 v14, v18, v12
	s_waitcnt lgkmcnt(0)
	v_add_f32_e32 v12, v12, v14
	ds_bpermute_b32 v14, v19, v12
	s_waitcnt lgkmcnt(0)
	v_add_f32_e32 v12, v12, v14
	ds_bpermute_b32 v14, v20, v12
	s_waitcnt lgkmcnt(0)
	v_add_f32_e32 v12, v12, v14
	ds_bpermute_b32 v14, v21, v12
	s_waitcnt lgkmcnt(0)
	v_add_f32_e32 v12, v12, v14
	ds_bpermute_b32 v14, v22, v12
	s_waitcnt lgkmcnt(0)
; __device__ __forceinline__ u32x4 pack8(const f32x4 v0, const f32x4 v1) { u32x4 w; w.x = cvt_pk_bf16(v0[0], v0[1]); w.y = cvt_pk_bf16(v0[2], v0[3]); w.z = cvt_pk_bf16(v1[0], v1[1]); w.w = cvt_pk_bf16(v1[2], v1[3]); return w; }
; __device__ __forceinline__ float silu_fast(float x) { return x * __builtin_amdgcn_rcpf(1.f + __expf(-x)); }
; #define LAS __attribute__((address_space(3)))
; __device__ __forceinline__ void conv_phase(LAS unsigned char* lds, const bf16_t* PROJ, const float* cw, const float* cb, const float* lg, const float* lb, bf16_t* MIXIN, int G, int tid) {
;     ...
;         for (int q = 0; q < 4; ++q) { const int tt = 4 * wave + q;
;             f32x4 a = *(const LAS f32x4*)(U + tt * 512 + 8 * lane), b = *(const LAS f32x4*)(U + tt * 512 + 8 * lane + 4);
;             const float mean = wave_sum((a[0] + a[1]) + (a[2] + a[3]) + (b[0] + b[1]) + (b[2] + b[3])) * (1.f / 512.f);
;             a = a - mean; b = b - mean;
;             const float var = wave_sum((a[0] * a[0] + a[1] * a[1]) + (a[2] * a[2] + a[3] * a[3]) + (b[0] * b[0] + b[1] * b[1]) + (b[2] * b[2] + b[3] * b[3])) * (1.f / 512.f);
;             const float rstd = rsqrtf(var + LN_EPS);
;             a = a * rstd * *(const f32x4*)(lg + 8 * lane) + *(const f32x4*)(lb + 8 * lane); b = b * rstd * *(const f32x4*)(lg + 8 * lane + 4) + *(const f32x4*)(lb + 8 * lane + 4);
; #pragma unroll
;             for (int x = 0; x < 4; ++x) { a[x] = pg8::silu_fast(a[x]); b[x] = pg8::silu_fast(b[x]); }
;             *(u32x4*)(MIXIN + (size_t)(row0 + tt) * D + 8 * lane) = pg8::pack8(a, b); }
;         __syncthreads();
	v_add_f32_e32 v12, v12, v14
	v_fmamk_f32 v12, v12, 0x3b000000, v173
	v_cmp_gt_f32_e32 vcc, s81, v12
	v_mul_f32_e32 v14, 0x4b800000, v12
	s_nop 0
	v_cndmask_b32_e32 v12, v12, v14, vcc
	v_rsq_f32_e32 v12, v12
	s_nop 0
	v_mul_f32_e32 v14, 0x45800000, v12
	v_cndmask_b32_e32 v12, v12, v14, vcc
	v_pk_mul_f32 v[14:15], v[4:5], v[12:13] op_sel_hi:[1,0]
	v_pk_mul_f32 v[16:17], v[6:7], v[12:13] op_sel_hi:[1,0]
	v_pk_mul_f32 v[0:1], v[0:1], v[12:13] op_sel_hi:[1,0]
	v_pk_mul_f32 v[2:3], v[2:3], v[12:13] op_sel_hi:[1,0]
	v_pk_fma_f32 v[0:1], v[100:101], v[0:1], v[108:109]
	v_pk_fma_f32 v[2:3], v[102:103], v[2:3], v[110:111]
	v_mul_f32_e32 v5, 0xbfb8aa3b, v0
	v_mul_f32_e32 v6, 0xbfb8aa3b, v1
	v_mul_f32_e32 v7, 0xbfb8aa3b, v2
	v_exp_f32_e32 v5, v5
	v_exp_f32_e32 v6, v6
	v_exp_f32_e32 v7, v7
	v_pk_fma_f32 v[16:17], v[106:107], v[16:17], v[114:115]
	v_add_f32_e32 v5, 1.0, v5
	v_add_f32_e32 v6, 1.0, v6
	v_add_f32_e32 v7, 1.0, v7
	v_rcp_f32_e32 v5, v5
	v_rcp_f32_e32 v6, v6
	v_rcp_f32_e32 v7, v7
	v_pk_fma_f32 v[14:15], v[104:105], v[14:15], v[112:113]
	v_mul_f32_e32 v5, v0, v5
	v_mul_f32_e32 v4, 0xbfb8aa3b, v14
	v_mul_f32_e32 v0, 0xbfb8aa3b, v15
	v_mul_f32_e32 v6, v1, v6
	v_mul_f32_e32 v1, 0xbfb8aa3b, v16
	v_mul_f32_e32 v7, v2, v7
	v_mul_f32_e32 v2, 0xbfb8aa3b, v17
	v_exp_f32_e32 v4, v4
	v_exp_f32_e32 v0, v0
	v_exp_f32_e32 v1, v1
	v_exp_f32_e32 v2, v2
	v_mul_f32_e32 v12, 0xbfb8aa3b, v3
	v_exp_f32_e32 v12, v12
	v_add_f32_e32 v4, 1.0, v4
	v_add_f32_e32 v0, 1.0, v0
	v_add_f32_e32 v1, 1.0, v1
	v_add_f32_e32 v2, 1.0, v2
	v_rcp_f32_e32 v4, v4
	v_rcp_f32_e32 v0, v0
	v_rcp_f32_e32 v1, v1
	v_rcp_f32_e32 v2, v2
	v_add_f32_e32 v12, 1.0, v12
	v_rcp_f32_e32 v12, v12
	v_mul_f32_e32 v4, v14, v4
	v_mul_f32_e32 v0, v15, v0
	v_mul_f32_e32 v1, v16, v1
	v_mul_f32_e32 v2, v17, v2
	v_mul_f32_e32 v3, v3, v12
	v_cvt_pk_bf16_f32 v0, v4, v0
	v_cvt_pk_bf16_f32 v1, v1, v2
	v_cvt_pk_bf16_f32 v2, v5, v6
	v_lshl_add_u64 v[4:5], v[10:11], 0, s[18:19]
	v_cvt_pk_bf16_f32 v3, v7, v3
	global_store_dwordx4 v[4:5], v[0:3], off
	ds_read_b128 v[4:7], v23 offset:6144
	ds_read_b128 v[0:3], v23 offset:6160
	s_waitcnt lgkmcnt(1)
	v_mov_b32_e32 v14, v5
	v_mov_b32_e32 v15, v6
	v_mov_b32_e32 v16, v4
	v_mov_b32_e32 v17, v7
	v_pk_add_f32 v[14:15], v[14:15], v[16:17]
	s_waitcnt lgkmcnt(0)
	v_mov_b32_e32 v16, v2
	v_mov_b32_e32 v17, v0
	v_mov_b32_e32 v24, v3
	v_mov_b32_e32 v25, v1
	v_pk_add_f32 v[16:17], v[16:17], v[24:25]
	v_add_f32_e32 v12, v14, v15
	v_add_f32_e32 v12, v12, v17
	v_add_f32_e32 v12, v16, v12
	ds_bpermute_b32 v14, v13, v12
	s_waitcnt lgkmcnt(0)
	v_add_f32_e32 v12, v12, v14
	ds_bpermute_b32 v14, v18, v12
	s_waitcnt lgkmcnt(0)
	v_add_f32_e32 v12, v12, v14
	ds_bpermute_b32 v14, v19, v12
	s_waitcnt lgkmcnt(0)
	v_add_f32_e32 v12, v12, v14
	ds_bpermute_b32 v14, v20, v12
	s_waitcnt lgkmcnt(0)
	v_add_f32_e32 v12, v12, v14
	ds_bpermute_b32 v14, v21, v12
	s_waitcnt lgkmcnt(0)
	v_add_f32_e32 v12, v12, v14
	ds_bpermute_b32 v14, v22, v12
	s_waitcnt lgkmcnt(0)
	v_add_f32_e32 v12, v12, v14
	v_fmamk_f32 v5, v12, 0xbb000000, v5
	v_fmamk_f32 v4, v12, 0xbb000000, v4
	v_fmamk_f32 v7, v12, 0xbb000000, v7
	v_fmac_f32_e32 v6, 0xbb000000, v12
	v_pk_mul_f32 v[14:15], v[6:7], v[6:7]
	v_pk_mul_f32 v[16:17], v[4:5], v[4:5]
	v_fmamk_f32 v1, v12, 0xbb000000, v1
	v_fmamk_f32 v0, v12, 0xbb000000, v0
	v_fmamk_f32 v3, v12, 0xbb000000, v3
	v_fmac_f32_e32 v2, 0xbb000000, v12
	v_pk_mov_b32 v[24:25], v[16:17], v[14:15] op_sel:[1,0]
	v_mov_b32_e32 v17, v15
	v_pk_add_f32 v[14:15], v[24:25], v[16:17]
	v_pk_mul_f32 v[16:17], v[2:3], v[2:3]
	v_pk_mul_f32 v[24:25], v[0:1], v[0:1]
	v_mov_b32_e32 v26, v16
	v_mov_b32_e32 v27, v24
	v_mov_b32_e32 v24, v17
	v_pk_add_f32 v[16:17], v[26:27], v[24:25]
	v_add_f32_e32 v12, v14, v15
	v_add_f32_e32 v12, v17, v12
	v_add_f32_e32 v12, v16, v12
	ds_bpermute_b32 v13, v13, v12
	s_waitcnt lgkmcnt(0)
	v_add_f32_e32 v12, v12, v13
	ds_bpermute_b32 v13, v18, v12
	s_waitcnt lgkmcnt(0)
	v_add_f32_e32 v12, v12, v13
	ds_bpermute_b32 v13, v19, v12
	s_waitcnt lgkmcnt(0)
	v_add_f32_e32 v12, v12, v13
	ds_bpermute_b32 v13, v20, v12
	s_waitcnt lgkmcnt(0)
	v_add_f32_e32 v12, v12, v13
	ds_bpermute_b32 v13, v21, v12
	s_waitcnt lgkmcnt(0)
	v_add_f32_e32 v12, v12, v13
	ds_bpermute_b32 v13, v22, v12
	s_waitcnt lgkmcnt(0)
	v_add_f32_e32 v12, v12, v13
	v_fmamk_f32 v12, v12, 0x3b000000, v173
	v_cmp_gt_f32_e32 vcc, s81, v12
	v_mul_f32_e32 v13, 0x4b800000, v12
	s_nop 0
	v_cndmask_b32_e32 v12, v12, v13, vcc
	v_rsq_f32_e32 v12, v12
	s_nop 0
	v_mul_f32_e32 v13, 0x45800000, v12
	v_cndmask_b32_e32 v12, v12, v13, vcc
	v_pk_mul_f32 v[14:15], v[4:5], v[12:13] op_sel_hi:[1,0]
	v_pk_mul_f32 v[16:17], v[6:7], v[12:13] op_sel_hi:[1,0]
	v_pk_mul_f32 v[0:1], v[0:1], v[12:13] op_sel_hi:[1,0]
	v_pk_mul_f32 v[2:3], v[2:3], v[12:13] op_sel_hi:[1,0]
	v_pk_fma_f32 v[0:1], v[100:101], v[0:1], v[108:109]
	v_pk_fma_f32 v[2:3], v[102:103], v[2:3], v[110:111]
	v_mul_f32_e32 v5, 0xbfb8aa3b, v0
	v_mul_f32_e32 v6, 0xbfb8aa3b, v1
	v_mul_f32_e32 v7, 0xbfb8aa3b, v2
	v_exp_f32_e32 v5, v5
	v_exp_f32_e32 v6, v6
	v_exp_f32_e32 v7, v7
	v_pk_fma_f32 v[16:17], v[106:107], v[16:17], v[114:115]
	v_add_f32_e32 v5, 1.0, v5
	v_add_f32_e32 v6, 1.0, v6
	v_add_f32_e32 v7, 1.0, v7
	v_rcp_f32_e32 v5, v5
	v_rcp_f32_e32 v6, v6
	v_rcp_f32_e32 v7, v7
	v_pk_fma_f32 v[14:15], v[104:105], v[14:15], v[112:113]
	v_mul_f32_e32 v5, v0, v5
	v_mul_f32_e32 v4, 0xbfb8aa3b, v14
	v_mul_f32_e32 v0, 0xbfb8aa3b, v15
	v_mul_f32_e32 v6, v1, v6
	v_mul_f32_e32 v1, 0xbfb8aa3b, v16
	v_mul_f32_e32 v7, v2, v7
	v_mul_f32_e32 v2, 0xbfb8aa3b, v17
	v_exp_f32_e32 v4, v4
	v_exp_f32_e32 v0, v0
	v_exp_f32_e32 v1, v1
	v_exp_f32_e32 v2, v2
	v_mul_f32_e32 v9, 0xbfb8aa3b, v3
	v_exp_f32_e32 v9, v9
	v_add_f32_e32 v4, 1.0, v4
	v_add_f32_e32 v0, 1.0, v0
	v_add_f32_e32 v1, 1.0, v1
	v_add_f32_e32 v2, 1.0, v2
	v_rcp_f32_e32 v4, v4
	v_rcp_f32_e32 v0, v0
	v_rcp_f32_e32 v1, v1
	v_rcp_f32_e32 v2, v2
	v_add_f32_e32 v9, 1.0, v9
	v_rcp_f32_e32 v9, v9
	v_mul_f32_e32 v4, v14, v4
	v_mul_f32_e32 v0, v15, v0
	v_mul_f32_e32 v1, v16, v1
	v_mul_f32_e32 v2, v17, v2
	v_cvt_pk_bf16_f32 v0, v4, v0
	v_cvt_pk_bf16_f32 v1, v1, v2
	v_cvt_pk_bf16_f32 v2, v5, v6
	v_lshl_add_u64 v[4:5], v[10:11], 0, s[4:5]
	v_readlane_b32 s4, v253, 9
	s_add_i32 s6, s6, s4
	v_mul_f32_e32 v3, v3, v9
	s_cmpk_lt_i32 s7, 0x400
	v_cvt_pk_bf16_f32 v3, v7, v3
	global_store_dwordx4 v[4:5], v[0:3], off
	s_barrier
	v_readlane_b32 s5, v253, 10
	s_cbranch_scc0 .LBB0_465
